# adds: first K-loop trip of each unit peeled (C=0 MFMAs replace 128 v_mov zeroing, preheader vmcnt(0) gone, first two waits counted past the epilogue stores) and hand-written step-15 phase (final row p
# speedup vs baseline: 1.0177x; 1.0042x over previous
; DI int lbid() { int b = (int)blockIdx.x; asm volatile("" : "+s"(b)); return b; }
; DI int lgdim() { int g = (int)gridDim.x; asm volatile("" : "+s"(g)); return g; }
; DI f32x4 bf4(v2u raw) { return (f32x4){bf2f((unsigned short)(raw.x & 0xffffu)), bf2f((unsigned short)(raw.x >> 16)), bf2f((unsigned short)(raw.y & 0xffffu)), bf2f((unsigned short)(raw.y >> 16))}; }
; template <bool HAS_MIX, bool WRITE_H, int NR, bool SRC16, bool DST16>
; DI void row_pass(const void* xsrc, const bf16* mix, void* xdst, float* rsd, size_t rstride, int rsstride, const float* gpost, int lane) {
;     ...
;     if (HAS_MIX) {
;         float rstd[NR];
; #pragma unroll
;         for (int rr = 0; rr < NR; ++rr) { float ss = 0.f;
; #pragma unroll
;             for (int j = 0; j < 8; ++j) { const f32x4 m = bf4(mr[rr][j]); ss += (m.x * m.x + m.y * m.y) + (m.z * m.z + m.w * m.w); }
;             rstd[rr] = 1.0f / sqrtf(wave_sum(ss) * (1.0f / D) + EPS); }
; template <bool FINAL>
; DI void phase_rowpass(const Params& P, int r, const float* gpost) {
;     int tid_l = threadIdx.x; asm volatile("" : "+v"(tid_l)); const int lane = tid_l & 63, wave = tid_l >> 6;
;     const bf16* MIX = (const bf16*)(P.ws + WS_MIX); bf16* X16 = (bf16*)(P.ws + WS_X16); float* RS = (float*)(P.ws + WS_RSTD);
;     float* xo = P.out + (size_t)r * MC * D;
;     const int NGW = lgdim() * 8;
;     for (int row = lbid() * 8 + wave; row < MC; row += 2 * NGW) {
;         const size_t o = (size_t)row * D;
;         void* dst = FINAL ? (void*)(xo + o) : (void*)(X16 + o);
;         if (row + NGW < MC) row_pass<true, !FINAL, 2, true, !FINAL>(X16 + o, MIX + o, dst, RS + row, (size_t)NGW * D, NGW, gpost, lane);
;         else row_pass<true, !FINAL, 1, true, !FINAL>(X16 + o, MIX + o, dst, RS + row, 0, 0, gpost, lane);
;     }
.LBB0_193:
	s_lshr_b32 s62, s34, 4
	s_and_b64 vcc, exec, s[6:7]
	s_cbranch_vccz .LBB0_217
	v_lshrrev_b32_e32 v128, 6, v152
	v_and_b32_e32 v131, 63, v152
	s_lshl_b32 s21, s64, 3
	v_readfirstlane_b32 s20, v128
	s_mov_b32 s24, 0x3a000000
	s_mov_b32 s25, 0x358637bd
	s_add_i32 s20, s21, s20
	s_lshl_b32 s21, s42, 3
	s_lshl_b32 s23, s21, 1
	s_add_i32 s22, s20, s21
	v_lshlrev_b32_e32 v132, 5, v131
	v_lshlrev_b32_e32 v131, 4, v131
	v_add_u32_e32 v133, 0x1000, v132
	s_add_u32 s0, s54, 0x32700000
	s_addc_u32 s1, s55, 0
	s_add_u32 s2, s54, 0x28700000
	s_addc_u32 s3, s55, 0
	s_lshl_b32 s4, s62, 27
	s_add_u32 s4, s14, s4
	s_addc_u32 s5, s15, 0
	s_add_u32 s6, s35, 0x6000
	s_addc_u32 s7, s36, 0
	global_load_dwordx4 v[0:3], v132, s[6:7]
	global_load_dwordx4 v[4:7], v132, s[6:7] offset:16
	global_load_dwordx4 v[8:11], v132, s[6:7] offset:2048
	global_load_dwordx4 v[12:15], v132, s[6:7] offset:2064
	global_load_dwordx4 v[16:19], v133, s[6:7]
	global_load_dwordx4 v[20:23], v133, s[6:7] offset:16
	global_load_dwordx4 v[24:27], v133, s[6:7] offset:2048
	global_load_dwordx4 v[28:31], v133, s[6:7] offset:2064
	s_lshl_b32 s26, s20, 12
	v_add_u32_e32 v134, s26, v131
	global_load_dwordx4 v[32:35], v134, s[0:1]
	global_load_dwordx4 v[36:39], v134, s[0:1] offset:1024
	global_load_dwordx4 v[40:43], v134, s[0:1] offset:2048
	global_load_dwordx4 v[44:47], v134, s[0:1] offset:3072
	global_load_dwordx4 v[48:51], v134, s[2:3] nt
	global_load_dwordx4 v[52:55], v134, s[2:3] offset:1024 nt
	global_load_dwordx4 v[56:59], v134, s[2:3] offset:2048 nt
	global_load_dwordx4 v[60:63], v134, s[2:3] offset:3072 nt
	s_lshl_b32 s26, s22, 12
	v_add_u32_e32 v135, s26, v131
	global_load_dwordx4 v[64:67], v135, s[0:1]
	global_load_dwordx4 v[68:71], v135, s[0:1] offset:1024
	global_load_dwordx4 v[72:75], v135, s[0:1] offset:2048
	global_load_dwordx4 v[76:79], v135, s[0:1] offset:3072
	global_load_dwordx4 v[80:83], v135, s[2:3] nt
	global_load_dwordx4 v[84:87], v135, s[2:3] offset:1024 nt
	global_load_dwordx4 v[88:91], v135, s[2:3] offset:2048 nt
	global_load_dwordx4 v[92:95], v135, s[2:3] offset:3072 nt
	s_waitcnt vmcnt(8)
.Lrf_top:
	s_add_i32 s26, s20, s23
	s_cmpk_lt_u32 s26, 0x4000
	s_cbranch_scc0 .Lrf_last
	s_waitcnt vmcnt(16)
	v_mov_b32_e32 v136, 0
	v_mov_b32_e32 v137, 0
	v_mov_b32_e32 v138, 0
	v_mov_b32_e32 v139, 0
	v_lshlrev_b32_e32 v96, 16, v48
	v_and_b32_e32 v97, 0xffff0000, v48
	v_lshlrev_b32_e32 v98, 16, v49
	v_and_b32_e32 v99, 0xffff0000, v49
	v_lshlrev_b32_e32 v100, 16, v50
	v_and_b32_e32 v101, 0xffff0000, v50
	v_lshlrev_b32_e32 v102, 16, v51
	v_and_b32_e32 v103, 0xffff0000, v51
	v_fmac_f32_e32 v136, v96, v96
	v_fmac_f32_e32 v137, v97, v97
	v_fmac_f32_e32 v138, v98, v98
	v_fmac_f32_e32 v139, v99, v99
	v_fmac_f32_e32 v136, v100, v100
	v_fmac_f32_e32 v137, v101, v101
	v_fmac_f32_e32 v138, v102, v102
	v_fmac_f32_e32 v139, v103, v103
	v_lshlrev_b32_e32 v104, 16, v52
	v_and_b32_e32 v105, 0xffff0000, v52
	v_lshlrev_b32_e32 v106, 16, v53
	v_and_b32_e32 v107, 0xffff0000, v53
	v_lshlrev_b32_e32 v108, 16, v54
	v_and_b32_e32 v109, 0xffff0000, v54
	v_lshlrev_b32_e32 v110, 16, v55
	v_and_b32_e32 v111, 0xffff0000, v55
	v_fmac_f32_e32 v136, v104, v104
	v_fmac_f32_e32 v137, v105, v105
	v_fmac_f32_e32 v138, v106, v106
	v_fmac_f32_e32 v139, v107, v107
	v_fmac_f32_e32 v136, v108, v108
	v_fmac_f32_e32 v137, v109, v109
	v_fmac_f32_e32 v138, v110, v110
	v_fmac_f32_e32 v139, v111, v111
	v_lshlrev_b32_e32 v112, 16, v56
	v_and_b32_e32 v113, 0xffff0000, v56
	v_lshlrev_b32_e32 v114, 16, v57
	v_and_b32_e32 v115, 0xffff0000, v57
	v_lshlrev_b32_e32 v116, 16, v58
	v_and_b32_e32 v117, 0xffff0000, v58
	v_lshlrev_b32_e32 v118, 16, v59
	v_and_b32_e32 v119, 0xffff0000, v59
	v_fmac_f32_e32 v136, v112, v112
	v_fmac_f32_e32 v137, v113, v113
	v_fmac_f32_e32 v138, v114, v114
	v_fmac_f32_e32 v139, v115, v115
	v_fmac_f32_e32 v136, v116, v116
	v_fmac_f32_e32 v137, v117, v117
	v_fmac_f32_e32 v138, v118, v118
	v_fmac_f32_e32 v139, v119, v119
	v_lshlrev_b32_e32 v120, 16, v60
	v_and_b32_e32 v121, 0xffff0000, v60
	v_lshlrev_b32_e32 v122, 16, v61
	v_and_b32_e32 v123, 0xffff0000, v61
	v_lshlrev_b32_e32 v124, 16, v62
	v_and_b32_e32 v125, 0xffff0000, v62
	v_lshlrev_b32_e32 v126, 16, v63
	v_and_b32_e32 v127, 0xffff0000, v63
	v_fmac_f32_e32 v136, v120, v120
	v_fmac_f32_e32 v137, v121, v121
	v_fmac_f32_e32 v138, v122, v122
	v_fmac_f32_e32 v139, v123, v123
	v_fmac_f32_e32 v136, v124, v124
	v_fmac_f32_e32 v137, v125, v125
	v_fmac_f32_e32 v138, v126, v126
	v_fmac_f32_e32 v139, v127, v127
	v_add_f32_e32 v136, v136, v137
	v_add_f32_e32 v138, v138, v139
	v_add_f32_e32 v136, v136, v138
	s_nop 1
	v_add_f32_dpp v136, v136, v136 quad_perm:[1,0,3,2] row_mask:0xf bank_mask:0xf
	s_nop 1
	v_add_f32_dpp v136, v136, v136 quad_perm:[2,3,0,1] row_mask:0xf bank_mask:0xf
	s_nop 1
	v_add_f32_dpp v136, v136, v136 row_half_mirror row_mask:0xf bank_mask:0xf
	s_nop 1
	v_add_f32_dpp v136, v136, v136 row_mirror row_mask:0xf bank_mask:0xf
	s_nop 1
	v_readlane_b32 s16, v136, 0
	v_readlane_b32 s17, v136, 16
	v_readlane_b32 s18, v136, 32
	v_readlane_b32 s19, v136, 48
	s_nop 1
	v_mov_b32_e32 v137, s16
	v_add_f32_e32 v137, s17, v137
	v_add_f32_e32 v137, s18, v137
	v_add_f32_e32 v137, s19, v137
	v_mov_b32_e32 v138, s25
	v_fma_f32 v137, v137, s24, v138
	v_rsq_f32_e32 v128, v137
	v_mul_f32_e32 v137, 0.5, v137
	v_mul_f32_e32 v138, v137, v128
	v_fma_f32 v138, -v138, v128, 0.5
	v_fma_f32 v128, v128, v138, v128
	s_lshl_b32 s26, s20, 13
	v_add_u32_e32 v136, s26, v132
	v_add_u32_e32 v137, s26, v133
	v_lshlrev_b32_e32 v138, 16, v32
	v_and_b32_e32 v139, 0xffff0000, v32
	v_mul_f32_e32 v96, v96, v128
	v_mul_f32_e32 v97, v97, v128
	v_fma_f32 v96, v96, v0, v138
	v_fma_f32 v97, v97, v1, v139
; DI unsigned pk2(float lo, float hi) { return pg8::cvt_pk_bf16(lo, hi); }
; DI f32x4 bf4(v2u raw) { return (f32x4){bf2f((unsigned short)(raw.x & 0xffffu)), bf2f((unsigned short)(raw.x >> 16)), bf2f((unsigned short)(raw.y & 0xffffu)), bf2f((unsigned short)(raw.y >> 16))}; }
; template <bool HAS_MIX, bool WRITE_H, int NR, bool SRC16, bool DST16>
; DI void row_pass(const void* xsrc, const bf16* mix, void* xdst, float* rsd, size_t rstride, int rsstride, const float* gpost, int lane) {
;     ...
; #pragma unroll
;         for (int j = 0; j < 8; ++j) { const f32x4 g = ((const f32x4*)gpost)[lane + 64 * j];
; #pragma unroll
;             for (int rr = 0; rr < NR; ++rr) { v[rr][j] = v[rr][j] + bf4(mr[rr][j]) * rstd[rr] * g;
;                 if (DST16) { v2u w; w.x = pk2(v[rr][j].x, v[rr][j].y); w.y = pk2(v[rr][j].z, v[rr][j].w); ((v2u*)((bf16*)xdst + rr * rstride))[lane + 64 * j] = w; }
;                 else __builtin_nontemporal_store(v[rr][j], (f32x4*)((float*)xdst + rr * rstride) + lane + 64 * j); } }
	v_lshlrev_b32_e32 v138, 16, v33
	v_and_b32_e32 v139, 0xffff0000, v33
	v_mul_f32_e32 v98, v98, v128
	v_mul_f32_e32 v99, v99, v128
	v_fma_f32 v98, v98, v2, v138
	v_fma_f32 v99, v99, v3, v139
	v_lshlrev_b32_e32 v138, 16, v34
	v_and_b32_e32 v139, 0xffff0000, v34
	v_mul_f32_e32 v100, v100, v128
	v_mul_f32_e32 v101, v101, v128
	v_fma_f32 v100, v100, v4, v138
	v_fma_f32 v101, v101, v5, v139
	v_lshlrev_b32_e32 v138, 16, v35
	v_and_b32_e32 v139, 0xffff0000, v35
	v_mul_f32_e32 v102, v102, v128
	v_mul_f32_e32 v103, v103, v128
	v_fma_f32 v102, v102, v6, v138
	v_fma_f32 v103, v103, v7, v139
	global_store_dwordx4 v136, v[96:99], s[4:5] nt
	global_store_dwordx4 v136, v[100:103], s[4:5] offset:16 nt
	v_lshlrev_b32_e32 v138, 16, v36
	v_and_b32_e32 v139, 0xffff0000, v36
	v_mul_f32_e32 v104, v104, v128
	v_mul_f32_e32 v105, v105, v128
	v_fma_f32 v104, v104, v8, v138
	v_fma_f32 v105, v105, v9, v139
	v_lshlrev_b32_e32 v138, 16, v37
	v_and_b32_e32 v139, 0xffff0000, v37
	v_mul_f32_e32 v106, v106, v128
	v_mul_f32_e32 v107, v107, v128
	v_fma_f32 v106, v106, v10, v138
	v_fma_f32 v107, v107, v11, v139
	v_lshlrev_b32_e32 v138, 16, v38
	v_and_b32_e32 v139, 0xffff0000, v38
	v_mul_f32_e32 v108, v108, v128
	v_mul_f32_e32 v109, v109, v128
	v_fma_f32 v108, v108, v12, v138
	v_fma_f32 v109, v109, v13, v139
	v_lshlrev_b32_e32 v138, 16, v39
	v_and_b32_e32 v139, 0xffff0000, v39
	v_mul_f32_e32 v110, v110, v128
	v_mul_f32_e32 v111, v111, v128
	v_fma_f32 v110, v110, v14, v138
	v_fma_f32 v111, v111, v15, v139
	global_store_dwordx4 v136, v[104:107], s[4:5] offset:2048 nt
	global_store_dwordx4 v136, v[108:111], s[4:5] offset:2064 nt
	v_lshlrev_b32_e32 v138, 16, v40
	v_and_b32_e32 v139, 0xffff0000, v40
	v_mul_f32_e32 v112, v112, v128
	v_mul_f32_e32 v113, v113, v128
	v_fma_f32 v112, v112, v16, v138
	v_fma_f32 v113, v113, v17, v139
	v_lshlrev_b32_e32 v138, 16, v41
	v_and_b32_e32 v139, 0xffff0000, v41
	v_mul_f32_e32 v114, v114, v128
	v_mul_f32_e32 v115, v115, v128
	v_fma_f32 v114, v114, v18, v138
	v_fma_f32 v115, v115, v19, v139
	v_lshlrev_b32_e32 v138, 16, v42
	v_and_b32_e32 v139, 0xffff0000, v42
	v_mul_f32_e32 v116, v116, v128
	v_mul_f32_e32 v117, v117, v128
	v_fma_f32 v116, v116, v20, v138
	v_fma_f32 v117, v117, v21, v139
	v_lshlrev_b32_e32 v138, 16, v43
	v_and_b32_e32 v139, 0xffff0000, v43
	v_mul_f32_e32 v118, v118, v128
	v_mul_f32_e32 v119, v119, v128
	v_fma_f32 v118, v118, v22, v138
	v_fma_f32 v119, v119, v23, v139
	global_store_dwordx4 v137, v[112:115], s[4:5] nt
	global_store_dwordx4 v137, v[116:119], s[4:5] offset:16 nt
	v_lshlrev_b32_e32 v138, 16, v44
	v_and_b32_e32 v139, 0xffff0000, v44
	v_mul_f32_e32 v120, v120, v128
	v_mul_f32_e32 v121, v121, v128
	v_fma_f32 v120, v120, v24, v138
	v_fma_f32 v121, v121, v25, v139
	v_lshlrev_b32_e32 v138, 16, v45
	v_and_b32_e32 v139, 0xffff0000, v45
	v_mul_f32_e32 v122, v122, v128
	v_mul_f32_e32 v123, v123, v128
	v_fma_f32 v122, v122, v26, v138
	v_fma_f32 v123, v123, v27, v139
	v_lshlrev_b32_e32 v138, 16, v46
	v_and_b32_e32 v139, 0xffff0000, v46
	v_mul_f32_e32 v124, v124, v128
	v_mul_f32_e32 v125, v125, v128
	v_fma_f32 v124, v124, v28, v138
	v_fma_f32 v125, v125, v29, v139
	v_lshlrev_b32_e32 v138, 16, v47
	v_and_b32_e32 v139, 0xffff0000, v47
	v_mul_f32_e32 v126, v126, v128
	v_mul_f32_e32 v127, v127, v128
	v_fma_f32 v126, v126, v30, v138
	v_fma_f32 v127, v127, v31, v139
	global_store_dwordx4 v137, v[120:123], s[4:5] offset:2048 nt
	global_store_dwordx4 v137, v[124:127], s[4:5] offset:2064 nt
	s_add_i32 s20, s20, s23
	s_lshl_b32 s26, s20, 12
	v_add_u32_e32 v134, s26, v131
	global_load_dwordx4 v[32:35], v134, s[0:1]
	global_load_dwordx4 v[36:39], v134, s[0:1] offset:1024
	global_load_dwordx4 v[40:43], v134, s[0:1] offset:2048
	global_load_dwordx4 v[44:47], v134, s[0:1] offset:3072
	global_load_dwordx4 v[48:51], v134, s[2:3] nt
	global_load_dwordx4 v[52:55], v134, s[2:3] offset:1024 nt
	global_load_dwordx4 v[56:59], v134, s[2:3] offset:2048 nt
	global_load_dwordx4 v[60:63], v134, s[2:3] offset:3072 nt
	s_waitcnt vmcnt(16)
	v_mov_b32_e32 v136, 0
	v_mov_b32_e32 v137, 0
	v_mov_b32_e32 v138, 0
	v_mov_b32_e32 v139, 0
	v_lshlrev_b32_e32 v96, 16, v80
	v_and_b32_e32 v97, 0xffff0000, v80
	v_lshlrev_b32_e32 v98, 16, v81
	v_and_b32_e32 v99, 0xffff0000, v81
	v_lshlrev_b32_e32 v100, 16, v82
	v_and_b32_e32 v101, 0xffff0000, v82
	v_lshlrev_b32_e32 v102, 16, v83
	v_and_b32_e32 v103, 0xffff0000, v83
	v_fmac_f32_e32 v136, v96, v96
	v_fmac_f32_e32 v137, v97, v97
	v_fmac_f32_e32 v138, v98, v98
	v_fmac_f32_e32 v139, v99, v99
	v_fmac_f32_e32 v136, v100, v100
	v_fmac_f32_e32 v137, v101, v101
	v_fmac_f32_e32 v138, v102, v102
	v_fmac_f32_e32 v139, v103, v103
	v_lshlrev_b32_e32 v104, 16, v84
	v_and_b32_e32 v105, 0xffff0000, v84
	v_lshlrev_b32_e32 v106, 16, v85
	v_and_b32_e32 v107, 0xffff0000, v85
	v_lshlrev_b32_e32 v108, 16, v86
	v_and_b32_e32 v109, 0xffff0000, v86
	v_lshlrev_b32_e32 v110, 16, v87
	v_and_b32_e32 v111, 0xffff0000, v87
	v_fmac_f32_e32 v136, v104, v104
	v_fmac_f32_e32 v137, v105, v105
	v_fmac_f32_e32 v138, v106, v106
	v_fmac_f32_e32 v139, v107, v107
	v_fmac_f32_e32 v136, v108, v108
	v_fmac_f32_e32 v137, v109, v109
	v_fmac_f32_e32 v138, v110, v110
	v_fmac_f32_e32 v139, v111, v111
	v_lshlrev_b32_e32 v112, 16, v88
	v_and_b32_e32 v113, 0xffff0000, v88
	v_lshlrev_b32_e32 v114, 16, v89
	v_and_b32_e32 v115, 0xffff0000, v89
	v_lshlrev_b32_e32 v116, 16, v90
	v_and_b32_e32 v117, 0xffff0000, v90
	v_lshlrev_b32_e32 v118, 16, v91
	v_and_b32_e32 v119, 0xffff0000, v91
	v_fmac_f32_e32 v136, v112, v112
	v_fmac_f32_e32 v137, v113, v113
	v_fmac_f32_e32 v138, v114, v114
	v_fmac_f32_e32 v139, v115, v115
	v_fmac_f32_e32 v136, v116, v116
	v_fmac_f32_e32 v137, v117, v117
; DI unsigned pk2(float lo, float hi) { return pg8::cvt_pk_bf16(lo, hi); }
; DI f32x4 bf4(v2u raw) { return (f32x4){bf2f((unsigned short)(raw.x & 0xffffu)), bf2f((unsigned short)(raw.x >> 16)), bf2f((unsigned short)(raw.y & 0xffffu)), bf2f((unsigned short)(raw.y >> 16))}; }
; template <bool HAS_MIX, bool WRITE_H, int NR, bool SRC16, bool DST16>
; DI void row_pass(const void* xsrc, const bf16* mix, void* xdst, float* rsd, size_t rstride, int rsstride, const float* gpost, int lane) {
;     ...
;     if (HAS_MIX) {
;         float rstd[NR];
; #pragma unroll
;         for (int rr = 0; rr < NR; ++rr) { float ss = 0.f;
; #pragma unroll
;             for (int j = 0; j < 8; ++j) { const f32x4 m = bf4(mr[rr][j]); ss += (m.x * m.x + m.y * m.y) + (m.z * m.z + m.w * m.w); }
;             rstd[rr] = 1.0f / sqrtf(wave_sum(ss) * (1.0f / D) + EPS); }
; #pragma unroll
;         for (int j = 0; j < 8; ++j) { const f32x4 g = ((const f32x4*)gpost)[lane + 64 * j];
; #pragma unroll
;             for (int rr = 0; rr < NR; ++rr) { v[rr][j] = v[rr][j] + bf4(mr[rr][j]) * rstd[rr] * g;
;                 if (DST16) { v2u w; w.x = pk2(v[rr][j].x, v[rr][j].y); w.y = pk2(v[rr][j].z, v[rr][j].w); ((v2u*)((bf16*)xdst + rr * rstride))[lane + 64 * j] = w; }
;                 else __builtin_nontemporal_store(v[rr][j], (f32x4*)((float*)xdst + rr * rstride) + lane + 64 * j); } }
	v_fmac_f32_e32 v138, v118, v118
	v_fmac_f32_e32 v139, v119, v119
	v_lshlrev_b32_e32 v120, 16, v92
	v_and_b32_e32 v121, 0xffff0000, v92
	v_lshlrev_b32_e32 v122, 16, v93
	v_and_b32_e32 v123, 0xffff0000, v93
	v_lshlrev_b32_e32 v124, 16, v94
	v_and_b32_e32 v125, 0xffff0000, v94
	v_lshlrev_b32_e32 v126, 16, v95
	v_and_b32_e32 v127, 0xffff0000, v95
	v_fmac_f32_e32 v136, v120, v120
	v_fmac_f32_e32 v137, v121, v121
	v_fmac_f32_e32 v138, v122, v122
	v_fmac_f32_e32 v139, v123, v123
	v_fmac_f32_e32 v136, v124, v124
	v_fmac_f32_e32 v137, v125, v125
	v_fmac_f32_e32 v138, v126, v126
	v_fmac_f32_e32 v139, v127, v127
	v_add_f32_e32 v136, v136, v137
	v_add_f32_e32 v138, v138, v139
	v_add_f32_e32 v136, v136, v138
	s_nop 1
	v_add_f32_dpp v136, v136, v136 quad_perm:[1,0,3,2] row_mask:0xf bank_mask:0xf
	s_nop 1
	v_add_f32_dpp v136, v136, v136 quad_perm:[2,3,0,1] row_mask:0xf bank_mask:0xf
	s_nop 1
	v_add_f32_dpp v136, v136, v136 row_half_mirror row_mask:0xf bank_mask:0xf
	s_nop 1
	v_add_f32_dpp v136, v136, v136 row_mirror row_mask:0xf bank_mask:0xf
	s_nop 1
	v_readlane_b32 s16, v136, 0
	v_readlane_b32 s17, v136, 16
	v_readlane_b32 s18, v136, 32
	v_readlane_b32 s19, v136, 48
	s_nop 1
	v_mov_b32_e32 v137, s16
	v_add_f32_e32 v137, s17, v137
	v_add_f32_e32 v137, s18, v137
	v_add_f32_e32 v137, s19, v137
	v_mov_b32_e32 v138, s25
	v_fma_f32 v137, v137, s24, v138
	v_rsq_f32_e32 v128, v137
	v_mul_f32_e32 v137, 0.5, v137
	v_mul_f32_e32 v138, v137, v128
	v_fma_f32 v138, -v138, v128, 0.5
	v_fma_f32 v128, v128, v138, v128
	s_lshl_b32 s26, s22, 13
	v_add_u32_e32 v136, s26, v132
	v_add_u32_e32 v137, s26, v133
	v_lshlrev_b32_e32 v138, 16, v64
	v_and_b32_e32 v139, 0xffff0000, v64
	v_mul_f32_e32 v96, v96, v128
	v_mul_f32_e32 v97, v97, v128
	v_fma_f32 v96, v96, v0, v138
	v_fma_f32 v97, v97, v1, v139
	v_lshlrev_b32_e32 v138, 16, v65
	v_and_b32_e32 v139, 0xffff0000, v65
	v_mul_f32_e32 v98, v98, v128
	v_mul_f32_e32 v99, v99, v128
	v_fma_f32 v98, v98, v2, v138
	v_fma_f32 v99, v99, v3, v139
	v_lshlrev_b32_e32 v138, 16, v66
	v_and_b32_e32 v139, 0xffff0000, v66
	v_mul_f32_e32 v100, v100, v128
	v_mul_f32_e32 v101, v101, v128
	v_fma_f32 v100, v100, v4, v138
	v_fma_f32 v101, v101, v5, v139
	v_lshlrev_b32_e32 v138, 16, v67
	v_and_b32_e32 v139, 0xffff0000, v67
	v_mul_f32_e32 v102, v102, v128
	v_mul_f32_e32 v103, v103, v128
	v_fma_f32 v102, v102, v6, v138
	v_fma_f32 v103, v103, v7, v139
	global_store_dwordx4 v136, v[96:99], s[4:5] nt
	global_store_dwordx4 v136, v[100:103], s[4:5] offset:16 nt
	v_lshlrev_b32_e32 v138, 16, v68
	v_and_b32_e32 v139, 0xffff0000, v68
	v_mul_f32_e32 v104, v104, v128
	v_mul_f32_e32 v105, v105, v128
	v_fma_f32 v104, v104, v8, v138
	v_fma_f32 v105, v105, v9, v139
	v_lshlrev_b32_e32 v138, 16, v69
	v_and_b32_e32 v139, 0xffff0000, v69
	v_mul_f32_e32 v106, v106, v128
	v_mul_f32_e32 v107, v107, v128
	v_fma_f32 v106, v106, v10, v138
	v_fma_f32 v107, v107, v11, v139
	v_lshlrev_b32_e32 v138, 16, v70
	v_and_b32_e32 v139, 0xffff0000, v70
	v_mul_f32_e32 v108, v108, v128
	v_mul_f32_e32 v109, v109, v128
	v_fma_f32 v108, v108, v12, v138
	v_fma_f32 v109, v109, v13, v139
	v_lshlrev_b32_e32 v138, 16, v71
	v_and_b32_e32 v139, 0xffff0000, v71
	v_mul_f32_e32 v110, v110, v128
	v_mul_f32_e32 v111, v111, v128
	v_fma_f32 v110, v110, v14, v138
	v_fma_f32 v111, v111, v15, v139
	global_store_dwordx4 v136, v[104:107], s[4:5] offset:2048 nt
	global_store_dwordx4 v136, v[108:111], s[4:5] offset:2064 nt
	v_lshlrev_b32_e32 v138, 16, v72
	v_and_b32_e32 v139, 0xffff0000, v72
	v_mul_f32_e32 v112, v112, v128
	v_mul_f32_e32 v113, v113, v128
	v_fma_f32 v112, v112, v16, v138
	v_fma_f32 v113, v113, v17, v139
	v_lshlrev_b32_e32 v138, 16, v73
	v_and_b32_e32 v139, 0xffff0000, v73
	v_mul_f32_e32 v114, v114, v128
	v_mul_f32_e32 v115, v115, v128
	v_fma_f32 v114, v114, v18, v138
	v_fma_f32 v115, v115, v19, v139
	v_lshlrev_b32_e32 v138, 16, v74
	v_and_b32_e32 v139, 0xffff0000, v74
	v_mul_f32_e32 v116, v116, v128
	v_mul_f32_e32 v117, v117, v128
	v_fma_f32 v116, v116, v20, v138
	v_fma_f32 v117, v117, v21, v139
	v_lshlrev_b32_e32 v138, 16, v75
	v_and_b32_e32 v139, 0xffff0000, v75
	v_mul_f32_e32 v118, v118, v128
	v_mul_f32_e32 v119, v119, v128
	v_fma_f32 v118, v118, v22, v138
	v_fma_f32 v119, v119, v23, v139
	global_store_dwordx4 v137, v[112:115], s[4:5] nt
	global_store_dwordx4 v137, v[116:119], s[4:5] offset:16 nt
	v_lshlrev_b32_e32 v138, 16, v76
	v_and_b32_e32 v139, 0xffff0000, v76
	v_mul_f32_e32 v120, v120, v128
	v_mul_f32_e32 v121, v121, v128
	v_fma_f32 v120, v120, v24, v138
	v_fma_f32 v121, v121, v25, v139
	v_lshlrev_b32_e32 v138, 16, v77
	v_and_b32_e32 v139, 0xffff0000, v77
	v_mul_f32_e32 v122, v122, v128
	v_mul_f32_e32 v123, v123, v128
	v_fma_f32 v122, v122, v26, v138
	v_fma_f32 v123, v123, v27, v139
	v_lshlrev_b32_e32 v138, 16, v78
	v_and_b32_e32 v139, 0xffff0000, v78
	v_mul_f32_e32 v124, v124, v128
	v_mul_f32_e32 v125, v125, v128
	v_fma_f32 v124, v124, v28, v138
	v_fma_f32 v125, v125, v29, v139
	v_lshlrev_b32_e32 v138, 16, v79
	v_and_b32_e32 v139, 0xffff0000, v79
	v_mul_f32_e32 v126, v126, v128
	v_mul_f32_e32 v127, v127, v128
	v_fma_f32 v126, v126, v30, v138
	v_fma_f32 v127, v127, v31, v139
	global_store_dwordx4 v137, v[120:123], s[4:5] offset:2048 nt
	global_store_dwordx4 v137, v[124:127], s[4:5] offset:2064 nt
	s_add_i32 s22, s22, s23
	s_lshl_b32 s26, s22, 12
	v_add_u32_e32 v135, s26, v131
	global_load_dwordx4 v[64:67], v135, s[0:1]
	global_load_dwordx4 v[68:71], v135, s[0:1] offset:1024
	global_load_dwordx4 v[72:75], v135, s[0:1] offset:2048
	global_load_dwordx4 v[76:79], v135, s[0:1] offset:3072
	global_load_dwordx4 v[80:83], v135, s[2:3] nt
	global_load_dwordx4 v[84:87], v135, s[2:3] offset:1024 nt
	global_load_dwordx4 v[88:91], v135, s[2:3] offset:2048 nt
	global_load_dwordx4 v[92:95], v135, s[2:3] offset:3072 nt
	s_branch .Lrf_top
; DI unsigned pk2(float lo, float hi) { return pg8::cvt_pk_bf16(lo, hi); }
; DI f32x4 bf4(v2u raw) { return (f32x4){bf2f((unsigned short)(raw.x & 0xffffu)), bf2f((unsigned short)(raw.x >> 16)), bf2f((unsigned short)(raw.y & 0xffffu)), bf2f((unsigned short)(raw.y >> 16))}; }
; template <bool HAS_MIX, bool WRITE_H, int NR, bool SRC16, bool DST16>
; DI void row_pass(const void* xsrc, const bf16* mix, void* xdst, float* rsd, size_t rstride, int rsstride, const float* gpost, int lane) {
;     ...
;     if (HAS_MIX) {
;         float rstd[NR];
; #pragma unroll
;         for (int rr = 0; rr < NR; ++rr) { float ss = 0.f;
; #pragma unroll
;             for (int j = 0; j < 8; ++j) { const f32x4 m = bf4(mr[rr][j]); ss += (m.x * m.x + m.y * m.y) + (m.z * m.z + m.w * m.w); }
;             rstd[rr] = 1.0f / sqrtf(wave_sum(ss) * (1.0f / D) + EPS); }
; #pragma unroll
;         for (int j = 0; j < 8; ++j) { const f32x4 g = ((const f32x4*)gpost)[lane + 64 * j];
; #pragma unroll
;             for (int rr = 0; rr < NR; ++rr) { v[rr][j] = v[rr][j] + bf4(mr[rr][j]) * rstd[rr] * g;
;                 if (DST16) { v2u w; w.x = pk2(v[rr][j].x, v[rr][j].y); w.y = pk2(v[rr][j].z, v[rr][j].w); ((v2u*)((bf16*)xdst + rr * rstride))[lane + 64 * j] = w; }
;                 else __builtin_nontemporal_store(v[rr][j], (f32x4*)((float*)xdst + rr * rstride) + lane + 64 * j); } }
.Lrf_last:
	s_waitcnt vmcnt(16)
	v_mov_b32_e32 v136, 0
	v_mov_b32_e32 v137, 0
	v_mov_b32_e32 v138, 0
	v_mov_b32_e32 v139, 0
	v_lshlrev_b32_e32 v96, 16, v48
	v_and_b32_e32 v97, 0xffff0000, v48
	v_lshlrev_b32_e32 v98, 16, v49
	v_and_b32_e32 v99, 0xffff0000, v49
	v_lshlrev_b32_e32 v100, 16, v50
	v_and_b32_e32 v101, 0xffff0000, v50
	v_lshlrev_b32_e32 v102, 16, v51
	v_and_b32_e32 v103, 0xffff0000, v51
	v_fmac_f32_e32 v136, v96, v96
	v_fmac_f32_e32 v137, v97, v97
	v_fmac_f32_e32 v138, v98, v98
	v_fmac_f32_e32 v139, v99, v99
	v_fmac_f32_e32 v136, v100, v100
	v_fmac_f32_e32 v137, v101, v101
	v_fmac_f32_e32 v138, v102, v102
	v_fmac_f32_e32 v139, v103, v103
	v_lshlrev_b32_e32 v104, 16, v52
	v_and_b32_e32 v105, 0xffff0000, v52
	v_lshlrev_b32_e32 v106, 16, v53
	v_and_b32_e32 v107, 0xffff0000, v53
	v_lshlrev_b32_e32 v108, 16, v54
	v_and_b32_e32 v109, 0xffff0000, v54
	v_lshlrev_b32_e32 v110, 16, v55
	v_and_b32_e32 v111, 0xffff0000, v55
	v_fmac_f32_e32 v136, v104, v104
	v_fmac_f32_e32 v137, v105, v105
	v_fmac_f32_e32 v138, v106, v106
	v_fmac_f32_e32 v139, v107, v107
	v_fmac_f32_e32 v136, v108, v108
	v_fmac_f32_e32 v137, v109, v109
	v_fmac_f32_e32 v138, v110, v110
	v_fmac_f32_e32 v139, v111, v111
	v_lshlrev_b32_e32 v112, 16, v56
	v_and_b32_e32 v113, 0xffff0000, v56
	v_lshlrev_b32_e32 v114, 16, v57
	v_and_b32_e32 v115, 0xffff0000, v57
	v_lshlrev_b32_e32 v116, 16, v58
	v_and_b32_e32 v117, 0xffff0000, v58
	v_lshlrev_b32_e32 v118, 16, v59
	v_and_b32_e32 v119, 0xffff0000, v59
	v_fmac_f32_e32 v136, v112, v112
	v_fmac_f32_e32 v137, v113, v113
	v_fmac_f32_e32 v138, v114, v114
	v_fmac_f32_e32 v139, v115, v115
	v_fmac_f32_e32 v136, v116, v116
	v_fmac_f32_e32 v137, v117, v117
	v_fmac_f32_e32 v138, v118, v118
	v_fmac_f32_e32 v139, v119, v119
	v_lshlrev_b32_e32 v120, 16, v60
	v_and_b32_e32 v121, 0xffff0000, v60
	v_lshlrev_b32_e32 v122, 16, v61
	v_and_b32_e32 v123, 0xffff0000, v61
	v_lshlrev_b32_e32 v124, 16, v62
	v_and_b32_e32 v125, 0xffff0000, v62
	v_lshlrev_b32_e32 v126, 16, v63
	v_and_b32_e32 v127, 0xffff0000, v63
	v_fmac_f32_e32 v136, v120, v120
	v_fmac_f32_e32 v137, v121, v121
	v_fmac_f32_e32 v138, v122, v122
	v_fmac_f32_e32 v139, v123, v123
	v_fmac_f32_e32 v136, v124, v124
	v_fmac_f32_e32 v137, v125, v125
	v_fmac_f32_e32 v138, v126, v126
	v_fmac_f32_e32 v139, v127, v127
	v_add_f32_e32 v136, v136, v137
	v_add_f32_e32 v138, v138, v139
	v_add_f32_e32 v136, v136, v138
	s_nop 1
	v_add_f32_dpp v136, v136, v136 quad_perm:[1,0,3,2] row_mask:0xf bank_mask:0xf
	s_nop 1
	v_add_f32_dpp v136, v136, v136 quad_perm:[2,3,0,1] row_mask:0xf bank_mask:0xf
	s_nop 1
	v_add_f32_dpp v136, v136, v136 row_half_mirror row_mask:0xf bank_mask:0xf
	s_nop 1
	v_add_f32_dpp v136, v136, v136 row_mirror row_mask:0xf bank_mask:0xf
	s_nop 1
	v_readlane_b32 s16, v136, 0
	v_readlane_b32 s17, v136, 16
	v_readlane_b32 s18, v136, 32
	v_readlane_b32 s19, v136, 48
	s_nop 1
	v_mov_b32_e32 v137, s16
	v_add_f32_e32 v137, s17, v137
	v_add_f32_e32 v137, s18, v137
	v_add_f32_e32 v137, s19, v137
	v_mov_b32_e32 v138, s25
	v_fma_f32 v137, v137, s24, v138
	v_rsq_f32_e32 v128, v137
	v_mul_f32_e32 v137, 0.5, v137
	v_mul_f32_e32 v138, v137, v128
	v_fma_f32 v138, -v138, v128, 0.5
	v_fma_f32 v128, v128, v138, v128
	s_lshl_b32 s26, s20, 13
	v_add_u32_e32 v136, s26, v132
	v_add_u32_e32 v137, s26, v133
	v_lshlrev_b32_e32 v138, 16, v32
	v_and_b32_e32 v139, 0xffff0000, v32
	v_mul_f32_e32 v96, v96, v128
	v_mul_f32_e32 v97, v97, v128
	v_fma_f32 v96, v96, v0, v138
	v_fma_f32 v97, v97, v1, v139
	v_lshlrev_b32_e32 v138, 16, v33
	v_and_b32_e32 v139, 0xffff0000, v33
	v_mul_f32_e32 v98, v98, v128
	v_mul_f32_e32 v99, v99, v128
	v_fma_f32 v98, v98, v2, v138
	v_fma_f32 v99, v99, v3, v139
	v_lshlrev_b32_e32 v138, 16, v34
	v_and_b32_e32 v139, 0xffff0000, v34
	v_mul_f32_e32 v100, v100, v128
	v_mul_f32_e32 v101, v101, v128
	v_fma_f32 v100, v100, v4, v138
	v_fma_f32 v101, v101, v5, v139
	v_lshlrev_b32_e32 v138, 16, v35
	v_and_b32_e32 v139, 0xffff0000, v35
	v_mul_f32_e32 v102, v102, v128
	v_mul_f32_e32 v103, v103, v128
	v_fma_f32 v102, v102, v6, v138
	v_fma_f32 v103, v103, v7, v139
	global_store_dwordx4 v136, v[96:99], s[4:5] nt
	global_store_dwordx4 v136, v[100:103], s[4:5] offset:16 nt
	v_lshlrev_b32_e32 v138, 16, v36
	v_and_b32_e32 v139, 0xffff0000, v36
	v_mul_f32_e32 v104, v104, v128
	v_mul_f32_e32 v105, v105, v128
	v_fma_f32 v104, v104, v8, v138
	v_fma_f32 v105, v105, v9, v139
	v_lshlrev_b32_e32 v138, 16, v37
	v_and_b32_e32 v139, 0xffff0000, v37
	v_mul_f32_e32 v106, v106, v128
	v_mul_f32_e32 v107, v107, v128
	v_fma_f32 v106, v106, v10, v138
	v_fma_f32 v107, v107, v11, v139
	v_lshlrev_b32_e32 v138, 16, v38
	v_and_b32_e32 v139, 0xffff0000, v38
	v_mul_f32_e32 v108, v108, v128
	v_mul_f32_e32 v109, v109, v128
	v_fma_f32 v108, v108, v12, v138
	v_fma_f32 v109, v109, v13, v139
	v_lshlrev_b32_e32 v138, 16, v39
	v_and_b32_e32 v139, 0xffff0000, v39
	v_mul_f32_e32 v110, v110, v128
	v_mul_f32_e32 v111, v111, v128
	v_fma_f32 v110, v110, v14, v138
	v_fma_f32 v111, v111, v15, v139
	global_store_dwordx4 v136, v[104:107], s[4:5] offset:2048 nt
	global_store_dwordx4 v136, v[108:111], s[4:5] offset:2064 nt
	v_lshlrev_b32_e32 v138, 16, v40
	v_and_b32_e32 v139, 0xffff0000, v40
	v_mul_f32_e32 v112, v112, v128
	v_mul_f32_e32 v113, v113, v128
	v_fma_f32 v112, v112, v16, v138
	v_fma_f32 v113, v113, v17, v139
	v_lshlrev_b32_e32 v138, 16, v41
	v_and_b32_e32 v139, 0xffff0000, v41
	v_mul_f32_e32 v114, v114, v128
	v_mul_f32_e32 v115, v115, v128
	v_fma_f32 v114, v114, v18, v138
	v_fma_f32 v115, v115, v19, v139
	v_lshlrev_b32_e32 v138, 16, v42
	v_and_b32_e32 v139, 0xffff0000, v42
	v_mul_f32_e32 v116, v116, v128
	v_mul_f32_e32 v117, v117, v128
	v_fma_f32 v116, v116, v20, v138
	v_fma_f32 v117, v117, v21, v139
	v_lshlrev_b32_e32 v138, 16, v43
	v_and_b32_e32 v139, 0xffff0000, v43
	v_mul_f32_e32 v118, v118, v128
	v_mul_f32_e32 v119, v119, v128
	v_fma_f32 v118, v118, v22, v138
	v_fma_f32 v119, v119, v23, v139
	global_store_dwordx4 v137, v[112:115], s[4:5] nt
	global_store_dwordx4 v137, v[116:119], s[4:5] offset:16 nt
	v_lshlrev_b32_e32 v138, 16, v44
	v_and_b32_e32 v139, 0xffff0000, v44
	v_mul_f32_e32 v120, v120, v128
	v_mul_f32_e32 v121, v121, v128
	v_fma_f32 v120, v120, v24, v138
	v_fma_f32 v121, v121, v25, v139
	v_lshlrev_b32_e32 v138, 16, v45
	v_and_b32_e32 v139, 0xffff0000, v45
	v_mul_f32_e32 v122, v122, v128
	v_mul_f32_e32 v123, v123, v128
	v_fma_f32 v122, v122, v26, v138
	v_fma_f32 v123, v123, v27, v139
	v_lshlrev_b32_e32 v138, 16, v46
	v_and_b32_e32 v139, 0xffff0000, v46
	v_mul_f32_e32 v124, v124, v128
	v_mul_f32_e32 v125, v125, v128
	v_fma_f32 v124, v124, v28, v138
	v_fma_f32 v125, v125, v29, v139
	v_lshlrev_b32_e32 v138, 16, v47
	v_and_b32_e32 v139, 0xffff0000, v47
	v_mul_f32_e32 v126, v126, v128
	v_mul_f32_e32 v127, v127, v128
	v_fma_f32 v126, v126, v30, v138
	v_fma_f32 v127, v127, v31, v139
	global_store_dwordx4 v137, v[120:123], s[4:5] offset:2048 nt
	global_store_dwordx4 v137, v[124:127], s[4:5] offset:2064 nt
	s_waitcnt vmcnt(8)
; DI unsigned pk2(float lo, float hi) { return pg8::cvt_pk_bf16(lo, hi); }
; DI f32x4 bf4(v2u raw) { return (f32x4){bf2f((unsigned short)(raw.x & 0xffffu)), bf2f((unsigned short)(raw.x >> 16)), bf2f((unsigned short)(raw.y & 0xffffu)), bf2f((unsigned short)(raw.y >> 16))}; }
; template <bool HAS_MIX, bool WRITE_H, int NR, bool SRC16, bool DST16>
; DI void row_pass(const void* xsrc, const bf16* mix, void* xdst, float* rsd, size_t rstride, int rsstride, const float* gpost, int lane) {
;     ...
;     if (HAS_MIX) {
;         float rstd[NR];
; #pragma unroll
;         for (int rr = 0; rr < NR; ++rr) { float ss = 0.f;
; #pragma unroll
;             for (int j = 0; j < 8; ++j) { const f32x4 m = bf4(mr[rr][j]); ss += (m.x * m.x + m.y * m.y) + (m.z * m.z + m.w * m.w); }
;             rstd[rr] = 1.0f / sqrtf(wave_sum(ss) * (1.0f / D) + EPS); }
; #pragma unroll
;         for (int j = 0; j < 8; ++j) { const f32x4 g = ((const f32x4*)gpost)[lane + 64 * j];
; #pragma unroll
;             for (int rr = 0; rr < NR; ++rr) { v[rr][j] = v[rr][j] + bf4(mr[rr][j]) * rstd[rr] * g;
;                 if (DST16) { v2u w; w.x = pk2(v[rr][j].x, v[rr][j].y); w.y = pk2(v[rr][j].z, v[rr][j].w); ((v2u*)((bf16*)xdst + rr * rstride))[lane + 64 * j] = w; }
;                 else __builtin_nontemporal_store(v[rr][j], (f32x4*)((float*)xdst + rr * rstride) + lane + 64 * j); } }
; __global__ void __launch_bounds__(512, 2) fwd_kernel(Params P) {
;     ...
;         else { phase_rowpass<true>(Q, r, gn + 3 * D); if (r + 1 < NROUND) phase_rowpass0(Q, r + 1); }
	v_mov_b32_e32 v136, 0
	v_mov_b32_e32 v137, 0
	v_mov_b32_e32 v138, 0
	v_mov_b32_e32 v139, 0
	v_lshlrev_b32_e32 v96, 16, v80
	v_and_b32_e32 v97, 0xffff0000, v80
	v_lshlrev_b32_e32 v98, 16, v81
	v_and_b32_e32 v99, 0xffff0000, v81
	v_lshlrev_b32_e32 v100, 16, v82
	v_and_b32_e32 v101, 0xffff0000, v82
	v_lshlrev_b32_e32 v102, 16, v83
	v_and_b32_e32 v103, 0xffff0000, v83
	v_fmac_f32_e32 v136, v96, v96
	v_fmac_f32_e32 v137, v97, v97
	v_fmac_f32_e32 v138, v98, v98
	v_fmac_f32_e32 v139, v99, v99
	v_fmac_f32_e32 v136, v100, v100
	v_fmac_f32_e32 v137, v101, v101
	v_fmac_f32_e32 v138, v102, v102
	v_fmac_f32_e32 v139, v103, v103
	v_lshlrev_b32_e32 v104, 16, v84
	v_and_b32_e32 v105, 0xffff0000, v84
	v_lshlrev_b32_e32 v106, 16, v85
	v_and_b32_e32 v107, 0xffff0000, v85
	v_lshlrev_b32_e32 v108, 16, v86
	v_and_b32_e32 v109, 0xffff0000, v86
	v_lshlrev_b32_e32 v110, 16, v87
	v_and_b32_e32 v111, 0xffff0000, v87
	v_fmac_f32_e32 v136, v104, v104
	v_fmac_f32_e32 v137, v105, v105
	v_fmac_f32_e32 v138, v106, v106
	v_fmac_f32_e32 v139, v107, v107
	v_fmac_f32_e32 v136, v108, v108
	v_fmac_f32_e32 v137, v109, v109
	v_fmac_f32_e32 v138, v110, v110
	v_fmac_f32_e32 v139, v111, v111
	v_lshlrev_b32_e32 v112, 16, v88
	v_and_b32_e32 v113, 0xffff0000, v88
	v_lshlrev_b32_e32 v114, 16, v89
	v_and_b32_e32 v115, 0xffff0000, v89
	v_lshlrev_b32_e32 v116, 16, v90
	v_and_b32_e32 v117, 0xffff0000, v90
	v_lshlrev_b32_e32 v118, 16, v91
	v_and_b32_e32 v119, 0xffff0000, v91
	v_fmac_f32_e32 v136, v112, v112
	v_fmac_f32_e32 v137, v113, v113
	v_fmac_f32_e32 v138, v114, v114
	v_fmac_f32_e32 v139, v115, v115
	v_fmac_f32_e32 v136, v116, v116
	v_fmac_f32_e32 v137, v117, v117
	v_fmac_f32_e32 v138, v118, v118
	v_fmac_f32_e32 v139, v119, v119
	v_lshlrev_b32_e32 v120, 16, v92
	v_and_b32_e32 v121, 0xffff0000, v92
	v_lshlrev_b32_e32 v122, 16, v93
	v_and_b32_e32 v123, 0xffff0000, v93
	v_lshlrev_b32_e32 v124, 16, v94
	v_and_b32_e32 v125, 0xffff0000, v94
	v_lshlrev_b32_e32 v126, 16, v95
	v_and_b32_e32 v127, 0xffff0000, v95
	v_fmac_f32_e32 v136, v120, v120
	v_fmac_f32_e32 v137, v121, v121
	v_fmac_f32_e32 v138, v122, v122
	v_fmac_f32_e32 v139, v123, v123
	v_fmac_f32_e32 v136, v124, v124
	v_fmac_f32_e32 v137, v125, v125
	v_fmac_f32_e32 v138, v126, v126
	v_fmac_f32_e32 v139, v127, v127
	v_add_f32_e32 v136, v136, v137
	v_add_f32_e32 v138, v138, v139
	v_add_f32_e32 v136, v136, v138
	s_nop 1
	v_add_f32_dpp v136, v136, v136 quad_perm:[1,0,3,2] row_mask:0xf bank_mask:0xf
	s_nop 1
	v_add_f32_dpp v136, v136, v136 quad_perm:[2,3,0,1] row_mask:0xf bank_mask:0xf
	s_nop 1
	v_add_f32_dpp v136, v136, v136 row_half_mirror row_mask:0xf bank_mask:0xf
	s_nop 1
	v_add_f32_dpp v136, v136, v136 row_mirror row_mask:0xf bank_mask:0xf
	s_nop 1
	v_readlane_b32 s16, v136, 0
	v_readlane_b32 s17, v136, 16
	v_readlane_b32 s18, v136, 32
	v_readlane_b32 s19, v136, 48
	s_nop 1
	v_mov_b32_e32 v137, s16
	v_add_f32_e32 v137, s17, v137
	v_add_f32_e32 v137, s18, v137
	v_add_f32_e32 v137, s19, v137
	v_mov_b32_e32 v138, s25
	v_fma_f32 v137, v137, s24, v138
	v_rsq_f32_e32 v128, v137
	v_mul_f32_e32 v137, 0.5, v137
	v_mul_f32_e32 v138, v137, v128
	v_fma_f32 v138, -v138, v128, 0.5
	v_fma_f32 v128, v128, v138, v128
	s_lshl_b32 s26, s22, 13
	v_add_u32_e32 v136, s26, v132
	v_add_u32_e32 v137, s26, v133
	v_lshlrev_b32_e32 v138, 16, v64
	v_and_b32_e32 v139, 0xffff0000, v64
	v_mul_f32_e32 v96, v96, v128
	v_mul_f32_e32 v97, v97, v128
	v_fma_f32 v96, v96, v0, v138
	v_fma_f32 v97, v97, v1, v139
	v_lshlrev_b32_e32 v138, 16, v65
	v_and_b32_e32 v139, 0xffff0000, v65
	v_mul_f32_e32 v98, v98, v128
	v_mul_f32_e32 v99, v99, v128
	v_fma_f32 v98, v98, v2, v138
	v_fma_f32 v99, v99, v3, v139
	v_lshlrev_b32_e32 v138, 16, v66
	v_and_b32_e32 v139, 0xffff0000, v66
	v_mul_f32_e32 v100, v100, v128
	v_mul_f32_e32 v101, v101, v128
	v_fma_f32 v100, v100, v4, v138
	v_fma_f32 v101, v101, v5, v139
	v_lshlrev_b32_e32 v138, 16, v67
	v_and_b32_e32 v139, 0xffff0000, v67
	v_mul_f32_e32 v102, v102, v128
	v_mul_f32_e32 v103, v103, v128
	v_fma_f32 v102, v102, v6, v138
	v_fma_f32 v103, v103, v7, v139
	global_store_dwordx4 v136, v[96:99], s[4:5] nt
	global_store_dwordx4 v136, v[100:103], s[4:5] offset:16 nt
	v_lshlrev_b32_e32 v138, 16, v68
	v_and_b32_e32 v139, 0xffff0000, v68
	v_mul_f32_e32 v104, v104, v128
	v_mul_f32_e32 v105, v105, v128
	v_fma_f32 v104, v104, v8, v138
	v_fma_f32 v105, v105, v9, v139
	v_lshlrev_b32_e32 v138, 16, v69
	v_and_b32_e32 v139, 0xffff0000, v69
	v_mul_f32_e32 v106, v106, v128
	v_mul_f32_e32 v107, v107, v128
	v_fma_f32 v106, v106, v10, v138
	v_fma_f32 v107, v107, v11, v139
	v_lshlrev_b32_e32 v138, 16, v70
	v_and_b32_e32 v139, 0xffff0000, v70
	v_mul_f32_e32 v108, v108, v128
	v_mul_f32_e32 v109, v109, v128
	v_fma_f32 v108, v108, v12, v138
	v_fma_f32 v109, v109, v13, v139
	v_lshlrev_b32_e32 v138, 16, v71
	v_and_b32_e32 v139, 0xffff0000, v71
	v_mul_f32_e32 v110, v110, v128
	v_mul_f32_e32 v111, v111, v128
	v_fma_f32 v110, v110, v14, v138
	v_fma_f32 v111, v111, v15, v139
	global_store_dwordx4 v136, v[104:107], s[4:5] offset:2048 nt
	global_store_dwordx4 v136, v[108:111], s[4:5] offset:2064 nt
	v_lshlrev_b32_e32 v138, 16, v72
	v_and_b32_e32 v139, 0xffff0000, v72
	v_mul_f32_e32 v112, v112, v128
	v_mul_f32_e32 v113, v113, v128
	v_fma_f32 v112, v112, v16, v138
	v_fma_f32 v113, v113, v17, v139
	v_lshlrev_b32_e32 v138, 16, v73
	v_and_b32_e32 v139, 0xffff0000, v73
	v_mul_f32_e32 v114, v114, v128
	v_mul_f32_e32 v115, v115, v128
	v_fma_f32 v114, v114, v18, v138
	v_fma_f32 v115, v115, v19, v139
	v_lshlrev_b32_e32 v138, 16, v74
	v_and_b32_e32 v139, 0xffff0000, v74
	v_mul_f32_e32 v116, v116, v128
	v_mul_f32_e32 v117, v117, v128
	v_fma_f32 v116, v116, v20, v138
	v_fma_f32 v117, v117, v21, v139
	v_lshlrev_b32_e32 v138, 16, v75
	v_and_b32_e32 v139, 0xffff0000, v75
	v_mul_f32_e32 v118, v118, v128
	v_mul_f32_e32 v119, v119, v128
	v_fma_f32 v118, v118, v22, v138
	v_fma_f32 v119, v119, v23, v139
	global_store_dwordx4 v137, v[112:115], s[4:5] nt
	global_store_dwordx4 v137, v[116:119], s[4:5] offset:16 nt
	v_lshlrev_b32_e32 v138, 16, v76
	v_and_b32_e32 v139, 0xffff0000, v76
	v_mul_f32_e32 v120, v120, v128
	v_mul_f32_e32 v121, v121, v128
	v_fma_f32 v120, v120, v24, v138
	v_fma_f32 v121, v121, v25, v139
	v_lshlrev_b32_e32 v138, 16, v77
	v_and_b32_e32 v139, 0xffff0000, v77
	v_mul_f32_e32 v122, v122, v128
	v_mul_f32_e32 v123, v123, v128
	v_fma_f32 v122, v122, v26, v138
	v_fma_f32 v123, v123, v27, v139
	v_lshlrev_b32_e32 v138, 16, v78
	v_and_b32_e32 v139, 0xffff0000, v78
	v_mul_f32_e32 v124, v124, v128
	v_mul_f32_e32 v125, v125, v128
	v_fma_f32 v124, v124, v28, v138
	v_fma_f32 v125, v125, v29, v139
	v_lshlrev_b32_e32 v138, 16, v79
	v_and_b32_e32 v139, 0xffff0000, v79
	v_mul_f32_e32 v126, v126, v128
	v_mul_f32_e32 v127, v127, v128
	v_fma_f32 v126, v126, v30, v138
	v_fma_f32 v127, v127, v31, v139
	global_store_dwordx4 v137, v[120:123], s[4:5] offset:2048 nt
	global_store_dwordx4 v137, v[124:127], s[4:5] offset:2064 nt
	s_cmp_gt_u32 s62, 2
	s_cbranch_scc1 .Lr0_done
; template <bool HAS_MIX, bool WRITE_H, int NR, bool SRC16, bool DST16>
; DI void row_pass(const void* xsrc, const bf16* mix, void* xdst, float* rsd, size_t rstride, int rsstride, const float* gpost, int lane) {
;     ...
;     if (!HAS_MIX && DST16) {
; #pragma unroll
;         for (int rr = 0; rr < NR; ++rr)
; #pragma unroll
;             for (int j = 0; j < 8; ++j) { v2u w; w.x = pk2(v[rr][j].x, v[rr][j].y); w.y = pk2(v[rr][j].z, v[rr][j].w); ((v2u*)((bf16*)xdst + rr * rstride))[lane + 64 * j] = w; }
;     }
;     if (HAS_MIX) {
;         float rstd[NR];
; #pragma unroll
;         for (int rr = 0; rr < NR; ++rr) { float ss = 0.f;
; #pragma unroll
;             for (int j = 0; j < 8; ++j) { const f32x4 m = bf4(mr[rr][j]); ss += (m.x * m.x + m.y * m.y) + (m.z * m.z + m.w * m.w); }
;             rstd[rr] = 1.0f / sqrtf(wave_sum(ss) * (1.0f / D) + EPS); }
; #pragma unroll
;         for (int j = 0; j < 8; ++j) { const f32x4 g = ((const f32x4*)gpost)[lane + 64 * j];
; #pragma unroll
;             for (int rr = 0; rr < NR; ++rr) { v[rr][j] = v[rr][j] + bf4(mr[rr][j]) * rstd[rr] * g;
;                 if (DST16) { v2u w; w.x = pk2(v[rr][j].x, v[rr][j].y); w.y = pk2(v[rr][j].z, v[rr][j].w); ((v2u*)((bf16*)xdst + rr * rstride))[lane + 64 * j] = w; }
;                 else __builtin_nontemporal_store(v[rr][j], (f32x4*)((float*)xdst + rr * rstride) + lane + 64 * j); } }
;     }
;     if (WRITE_H) {
; #pragma unroll
;         for (int rr = 0; rr < NR; ++rr) { float ss = 0.f;
; #pragma unroll
;             for (int j = 0; j < 8; ++j) ss += (v[rr][j].x * v[rr][j].x + v[rr][j].y * v[rr][j].y) + (v[rr][j].z * v[rr][j].z + v[rr][j].w * v[rr][j].w);
; DI void phase_rowpass0(const Params& P, int r) {
;     int tid_l = threadIdx.x; asm volatile("" : "+v"(tid_l)); const int lane = tid_l & 63, wave = tid_l >> 6;
;     bf16* X16 = (bf16*)(P.ws + WS_X16); float* RS = (float*)(P.ws + WS_RSTD); const float* xb = xin_row(P, r * MC);
;     const int NGW = lgdim() * 8;
;     for (int row = lbid() * 8 + wave; row < MC; row += 2 * NGW) {
;         const size_t o = (size_t)row * D;
;         if (row + NGW < MC) row_pass<false, true, 2, false, true>(xb + o, nullptr, X16 + o, RS + row, (size_t)NGW * D, NGW, nullptr, lane);
;         else row_pass<false, true, 1, false, true>(xb + o, nullptr, X16 + o, RS + row, 0, 0, nullptr, lane);
;     }
	v_lshrrev_b32_e32 v128, 6, v152
	v_and_b32_e32 v131, 63, v152
	s_lshl_b32 s21, s64, 3
	v_readfirstlane_b32 s20, v128
	s_mov_b32 s24, 0x3a000000
	s_mov_b32 s25, 0x358637bd
	s_add_i32 s20, s21, s20
	s_lshl_b32 s21, s42, 3
	s_lshl_b32 s23, s21, 1
	s_add_i32 s22, s20, s21
	v_lshlrev_b32_e32 v132, 5, v131
	v_lshlrev_b32_e32 v131, 4, v131
	v_add_u32_e32 v133, 0x1000, v132
	s_lshl_b32 s26, s62, 27
	s_add_u32 s0, s10, s26
	s_addc_u32 s1, s11, 0
	s_sub_u32 s0, s0, 0x8000000
	s_subb_u32 s1, s1, 0
	s_add_u32 s2, s12, 0x8000000
	s_addc_u32 s3, s13, 0
	s_cmp_eq_u32 s62, 0
	s_cselect_b32 s0, s2, s0
	s_cselect_b32 s1, s3, s1
	s_add_u32 s2, s54, 0x32700000
	s_addc_u32 s3, s55, 0
	s_add_u32 s4, s54, 0x10000
	s_addc_u32 s5, s55, 0
	s_lshl_b32 s26, s20, 13
	v_add_u32_e32 v96, s26, v132
	v_add_u32_e32 v97, s26, v133
	global_load_dwordx4 v[32:35], v96, s[0:1] nt
	global_load_dwordx4 v[36:39], v96, s[0:1] offset:16 nt
	global_load_dwordx4 v[40:43], v96, s[0:1] offset:2048 nt
	global_load_dwordx4 v[44:47], v96, s[0:1] offset:2064 nt
	global_load_dwordx4 v[48:51], v97, s[0:1] nt
	global_load_dwordx4 v[52:55], v97, s[0:1] offset:16 nt
	global_load_dwordx4 v[56:59], v97, s[0:1] offset:2048 nt
	global_load_dwordx4 v[60:63], v97, s[0:1] offset:2064 nt
	s_lshl_b32 s26, s22, 13
	v_add_u32_e32 v98, s26, v132
	v_add_u32_e32 v99, s26, v133
	global_load_dwordx4 v[64:67], v98, s[0:1] nt
	global_load_dwordx4 v[68:71], v98, s[0:1] offset:16 nt
	global_load_dwordx4 v[72:75], v98, s[0:1] offset:2048 nt
	global_load_dwordx4 v[76:79], v98, s[0:1] offset:2064 nt
	global_load_dwordx4 v[80:83], v99, s[0:1] nt
	global_load_dwordx4 v[84:87], v99, s[0:1] offset:16 nt
	global_load_dwordx4 v[88:91], v99, s[0:1] offset:2048 nt
	global_load_dwordx4 v[92:95], v99, s[0:1] offset:2064 nt
	s_waitcnt vmcnt(8)
.Lr0_top:
	s_add_i32 s26, s20, s23
	s_cmpk_lt_u32 s26, 0x4000
	s_cbranch_scc0 .Lr0_last
	s_waitcnt vmcnt(13)
	v_mov_b32_e32 v136, 0
	v_mov_b32_e32 v137, 0
	v_mov_b32_e32 v138, 0
	v_mov_b32_e32 v139, 0
	s_lshl_b32 s26, s20, 12
	v_add_u32_e32 v134, s26, v131
	v_fmac_f32_e32 v136, v32, v32
	v_fmac_f32_e32 v137, v33, v33
	v_fmac_f32_e32 v138, v34, v34
	v_fmac_f32_e32 v139, v35, v35
	v_fmac_f32_e32 v136, v36, v36
	v_fmac_f32_e32 v137, v37, v37
	v_fmac_f32_e32 v138, v38, v38
	v_fmac_f32_e32 v139, v39, v39
	v_cvt_pk_bf16_f32 v32, v32, v33
	v_cvt_pk_bf16_f32 v33, v34, v35
	v_cvt_pk_bf16_f32 v34, v36, v37
	v_cvt_pk_bf16_f32 v35, v38, v39
	global_store_dwordx4 v134, v[32:35], s[2:3]
	v_fmac_f32_e32 v136, v40, v40
	v_fmac_f32_e32 v137, v41, v41
	v_fmac_f32_e32 v138, v42, v42
	v_fmac_f32_e32 v139, v43, v43
	v_fmac_f32_e32 v136, v44, v44
	v_fmac_f32_e32 v137, v45, v45
	v_fmac_f32_e32 v138, v46, v46
	v_fmac_f32_e32 v139, v47, v47
	v_cvt_pk_bf16_f32 v40, v40, v41
	v_cvt_pk_bf16_f32 v41, v42, v43
	v_cvt_pk_bf16_f32 v42, v44, v45
	v_cvt_pk_bf16_f32 v43, v46, v47
	global_store_dwordx4 v134, v[40:43], s[2:3] offset:1024
	v_fmac_f32_e32 v136, v48, v48
	v_fmac_f32_e32 v137, v49, v49
	v_fmac_f32_e32 v138, v50, v50
	v_fmac_f32_e32 v139, v51, v51
	v_fmac_f32_e32 v136, v52, v52
	v_fmac_f32_e32 v137, v53, v53
	v_fmac_f32_e32 v138, v54, v54
	v_fmac_f32_e32 v139, v55, v55
	v_cvt_pk_bf16_f32 v48, v48, v49
	v_cvt_pk_bf16_f32 v49, v50, v51
	v_cvt_pk_bf16_f32 v50, v52, v53
	v_cvt_pk_bf16_f32 v51, v54, v55
	global_store_dwordx4 v134, v[48:51], s[2:3] offset:2048
	v_fmac_f32_e32 v136, v56, v56
	v_fmac_f32_e32 v137, v57, v57
	v_fmac_f32_e32 v138, v58, v58
	v_fmac_f32_e32 v139, v59, v59
	v_fmac_f32_e32 v136, v60, v60
	v_fmac_f32_e32 v137, v61, v61
	v_fmac_f32_e32 v138, v62, v62
	v_fmac_f32_e32 v139, v63, v63
	v_cvt_pk_bf16_f32 v56, v56, v57
	v_cvt_pk_bf16_f32 v57, v58, v59
	v_cvt_pk_bf16_f32 v58, v60, v61
	v_cvt_pk_bf16_f32 v59, v62, v63
	global_store_dwordx4 v134, v[56:59], s[2:3] offset:3072
	v_add_f32_e32 v136, v136, v137
	v_add_f32_e32 v138, v138, v139
	v_add_f32_e32 v136, v136, v138
	s_nop 1
	v_add_f32_dpp v136, v136, v136 quad_perm:[1,0,3,2] row_mask:0xf bank_mask:0xf
	s_nop 1
	v_add_f32_dpp v136, v136, v136 quad_perm:[2,3,0,1] row_mask:0xf bank_mask:0xf
	s_nop 1
	v_add_f32_dpp v136, v136, v136 row_half_mirror row_mask:0xf bank_mask:0xf
	s_nop 1
	v_add_f32_dpp v136, v136, v136 row_mirror row_mask:0xf bank_mask:0xf
	s_nop 1
	v_readlane_b32 s16, v136, 0
	v_readlane_b32 s17, v136, 16
	v_readlane_b32 s18, v136, 32
	v_readlane_b32 s19, v136, 48
	s_nop 1
	v_mov_b32_e32 v137, s16
	v_add_f32_e32 v137, s17, v137
	v_add_f32_e32 v137, s18, v137
	v_add_f32_e32 v137, s19, v137
	v_mov_b32_e32 v138, s25
	v_fma_f32 v137, v137, s24, v138
	v_rsq_f32_e32 v128, v137
	v_mul_f32_e32 v137, 0.5, v137
	v_mul_f32_e32 v138, v137, v128
	v_fma_f32 v138, -v138, v128, 0.5
	v_fma_f32 v128, v128, v138, v128
	s_lshl_b32 s26, s20, 2
	s_add_u32 s26, s4, s26
	s_addc_u32 s27, s5, 0
	v_mov_b32_e32 v139, 0
	s_mov_b64 exec, 1
	global_store_dword v139, v128, s[26:27]
	s_mov_b64 exec, -1
	s_add_i32 s20, s20, s23
	s_lshl_b32 s26, s20, 13
	v_add_u32_e32 v96, s26, v132
	v_add_u32_e32 v97, s26, v133
	global_load_dwordx4 v[32:35], v96, s[0:1] nt
	global_load_dwordx4 v[36:39], v96, s[0:1] offset:16 nt
	global_load_dwordx4 v[40:43], v96, s[0:1] offset:2048 nt
	global_load_dwordx4 v[44:47], v96, s[0:1] offset:2064 nt
	global_load_dwordx4 v[48:51], v97, s[0:1] nt
	global_load_dwordx4 v[52:55], v97, s[0:1] offset:16 nt
	global_load_dwordx4 v[56:59], v97, s[0:1] offset:2048 nt
	global_load_dwordx4 v[60:63], v97, s[0:1] offset:2064 nt
	s_waitcnt vmcnt(13)
; DI unsigned pk2(float lo, float hi) { return pg8::cvt_pk_bf16(lo, hi); }
; DI f32x4 bf4(v2u raw) { return (f32x4){bf2f((unsigned short)(raw.x & 0xffffu)), bf2f((unsigned short)(raw.x >> 16)), bf2f((unsigned short)(raw.y & 0xffffu)), bf2f((unsigned short)(raw.y >> 16))}; }
; template <bool HAS_MIX, bool WRITE_H, int NR, bool SRC16, bool DST16>
; DI void row_pass(const void* xsrc, const bf16* mix, void* xdst, float* rsd, size_t rstride, int rsstride, const float* gpost, int lane) {
;     ...
;     if (!HAS_MIX && DST16) {
; #pragma unroll
;         for (int rr = 0; rr < NR; ++rr)
; #pragma unroll
;             for (int j = 0; j < 8; ++j) { v2u w; w.x = pk2(v[rr][j].x, v[rr][j].y); w.y = pk2(v[rr][j].z, v[rr][j].w); ((v2u*)((bf16*)xdst + rr * rstride))[lane + 64 * j] = w; }
;     }
;     if (HAS_MIX) {
;         float rstd[NR];
; #pragma unroll
;         for (int rr = 0; rr < NR; ++rr) { float ss = 0.f;
; #pragma unroll
;             for (int j = 0; j < 8; ++j) { const f32x4 m = bf4(mr[rr][j]); ss += (m.x * m.x + m.y * m.y) + (m.z * m.z + m.w * m.w); }
;             rstd[rr] = 1.0f / sqrtf(wave_sum(ss) * (1.0f / D) + EPS); }
; #pragma unroll
;         for (int j = 0; j < 8; ++j) { const f32x4 g = ((const f32x4*)gpost)[lane + 64 * j];
; #pragma unroll
;             for (int rr = 0; rr < NR; ++rr) { v[rr][j] = v[rr][j] + bf4(mr[rr][j]) * rstd[rr] * g;
;                 if (DST16) { v2u w; w.x = pk2(v[rr][j].x, v[rr][j].y); w.y = pk2(v[rr][j].z, v[rr][j].w); ((v2u*)((bf16*)xdst + rr * rstride))[lane + 64 * j] = w; }
;                 else __builtin_nontemporal_store(v[rr][j], (f32x4*)((float*)xdst + rr * rstride) + lane + 64 * j); } }
;     }
;     if (WRITE_H) {
; #pragma unroll
;         for (int rr = 0; rr < NR; ++rr) { float ss = 0.f;
; #pragma unroll
;             for (int j = 0; j < 8; ++j) ss += (v[rr][j].x * v[rr][j].x + v[rr][j].y * v[rr][j].y) + (v[rr][j].z * v[rr][j].z + v[rr][j].w * v[rr][j].w);
;             const float rstd = 1.0f / sqrtf(wave_sum(ss) * (1.0f / D) + EPS);
;             if (lane == 0) rsd[rr * rsstride] = rstd; }
	v_mov_b32_e32 v136, 0
	v_mov_b32_e32 v137, 0
	v_mov_b32_e32 v138, 0
	v_mov_b32_e32 v139, 0
	s_lshl_b32 s26, s22, 12
	v_add_u32_e32 v135, s26, v131
	v_fmac_f32_e32 v136, v64, v64
	v_fmac_f32_e32 v137, v65, v65
	v_fmac_f32_e32 v138, v66, v66
	v_fmac_f32_e32 v139, v67, v67
	v_fmac_f32_e32 v136, v68, v68
	v_fmac_f32_e32 v137, v69, v69
	v_fmac_f32_e32 v138, v70, v70
	v_fmac_f32_e32 v139, v71, v71
	v_cvt_pk_bf16_f32 v64, v64, v65
	v_cvt_pk_bf16_f32 v65, v66, v67
	v_cvt_pk_bf16_f32 v66, v68, v69
	v_cvt_pk_bf16_f32 v67, v70, v71
	global_store_dwordx4 v135, v[64:67], s[2:3]
	v_fmac_f32_e32 v136, v72, v72
	v_fmac_f32_e32 v137, v73, v73
	v_fmac_f32_e32 v138, v74, v74
	v_fmac_f32_e32 v139, v75, v75
	v_fmac_f32_e32 v136, v76, v76
	v_fmac_f32_e32 v137, v77, v77
	v_fmac_f32_e32 v138, v78, v78
	v_fmac_f32_e32 v139, v79, v79
	v_cvt_pk_bf16_f32 v72, v72, v73
	v_cvt_pk_bf16_f32 v73, v74, v75
	v_cvt_pk_bf16_f32 v74, v76, v77
	v_cvt_pk_bf16_f32 v75, v78, v79
	global_store_dwordx4 v135, v[72:75], s[2:3] offset:1024
	v_fmac_f32_e32 v136, v80, v80
	v_fmac_f32_e32 v137, v81, v81
	v_fmac_f32_e32 v138, v82, v82
	v_fmac_f32_e32 v139, v83, v83
	v_fmac_f32_e32 v136, v84, v84
	v_fmac_f32_e32 v137, v85, v85
	v_fmac_f32_e32 v138, v86, v86
	v_fmac_f32_e32 v139, v87, v87
	v_cvt_pk_bf16_f32 v80, v80, v81
	v_cvt_pk_bf16_f32 v81, v82, v83
	v_cvt_pk_bf16_f32 v82, v84, v85
	v_cvt_pk_bf16_f32 v83, v86, v87
	global_store_dwordx4 v135, v[80:83], s[2:3] offset:2048
	v_fmac_f32_e32 v136, v88, v88
	v_fmac_f32_e32 v137, v89, v89
	v_fmac_f32_e32 v138, v90, v90
	v_fmac_f32_e32 v139, v91, v91
	v_fmac_f32_e32 v136, v92, v92
	v_fmac_f32_e32 v137, v93, v93
	v_fmac_f32_e32 v138, v94, v94
	v_fmac_f32_e32 v139, v95, v95
	v_cvt_pk_bf16_f32 v88, v88, v89
	v_cvt_pk_bf16_f32 v89, v90, v91
	v_cvt_pk_bf16_f32 v90, v92, v93
	v_cvt_pk_bf16_f32 v91, v94, v95
	global_store_dwordx4 v135, v[88:91], s[2:3] offset:3072
	v_add_f32_e32 v136, v136, v137
	v_add_f32_e32 v138, v138, v139
	v_add_f32_e32 v136, v136, v138
	s_nop 1
	v_add_f32_dpp v136, v136, v136 quad_perm:[1,0,3,2] row_mask:0xf bank_mask:0xf
	s_nop 1
	v_add_f32_dpp v136, v136, v136 quad_perm:[2,3,0,1] row_mask:0xf bank_mask:0xf
	s_nop 1
	v_add_f32_dpp v136, v136, v136 row_half_mirror row_mask:0xf bank_mask:0xf
	s_nop 1
	v_add_f32_dpp v136, v136, v136 row_mirror row_mask:0xf bank_mask:0xf
	s_nop 1
	v_readlane_b32 s16, v136, 0
	v_readlane_b32 s17, v136, 16
	v_readlane_b32 s18, v136, 32
	v_readlane_b32 s19, v136, 48
	s_nop 1
	v_mov_b32_e32 v137, s16
	v_add_f32_e32 v137, s17, v137
	v_add_f32_e32 v137, s18, v137
	v_add_f32_e32 v137, s19, v137
	v_mov_b32_e32 v138, s25
	v_fma_f32 v137, v137, s24, v138
	v_rsq_f32_e32 v128, v137
	v_mul_f32_e32 v137, 0.5, v137
	v_mul_f32_e32 v138, v137, v128
	v_fma_f32 v138, -v138, v128, 0.5
	v_fma_f32 v128, v128, v138, v128
	s_lshl_b32 s26, s22, 2
	s_add_u32 s26, s4, s26
	s_addc_u32 s27, s5, 0
	v_mov_b32_e32 v139, 0
	s_mov_b64 exec, 1
	global_store_dword v139, v128, s[26:27]
	s_mov_b64 exec, -1
	s_add_i32 s22, s22, s23
	s_lshl_b32 s26, s22, 13
	v_add_u32_e32 v98, s26, v132
	v_add_u32_e32 v99, s26, v133
	global_load_dwordx4 v[64:67], v98, s[0:1] nt
	global_load_dwordx4 v[68:71], v98, s[0:1] offset:16 nt
	global_load_dwordx4 v[72:75], v98, s[0:1] offset:2048 nt
	global_load_dwordx4 v[76:79], v98, s[0:1] offset:2064 nt
	global_load_dwordx4 v[80:83], v99, s[0:1] nt
	global_load_dwordx4 v[84:87], v99, s[0:1] offset:16 nt
	global_load_dwordx4 v[88:91], v99, s[0:1] offset:2048 nt
	global_load_dwordx4 v[92:95], v99, s[0:1] offset:2064 nt
	s_branch .Lr0_top
; DI unsigned pk2(float lo, float hi) { return pg8::cvt_pk_bf16(lo, hi); }
; DI f32x4 bf4(v2u raw) { return (f32x4){bf2f((unsigned short)(raw.x & 0xffffu)), bf2f((unsigned short)(raw.x >> 16)), bf2f((unsigned short)(raw.y & 0xffffu)), bf2f((unsigned short)(raw.y >> 16))}; }
; template <bool HAS_MIX, bool WRITE_H, int NR, bool SRC16, bool DST16>
; DI void row_pass(const void* xsrc, const bf16* mix, void* xdst, float* rsd, size_t rstride, int rsstride, const float* gpost, int lane) {
;     ...
;     if (!HAS_MIX && DST16) {
; #pragma unroll
;         for (int rr = 0; rr < NR; ++rr)
; #pragma unroll
;             for (int j = 0; j < 8; ++j) { v2u w; w.x = pk2(v[rr][j].x, v[rr][j].y); w.y = pk2(v[rr][j].z, v[rr][j].w); ((v2u*)((bf16*)xdst + rr * rstride))[lane + 64 * j] = w; }
;     }
;     if (HAS_MIX) {
;         float rstd[NR];
; #pragma unroll
;         for (int rr = 0; rr < NR; ++rr) { float ss = 0.f;
; #pragma unroll
;             for (int j = 0; j < 8; ++j) { const f32x4 m = bf4(mr[rr][j]); ss += (m.x * m.x + m.y * m.y) + (m.z * m.z + m.w * m.w); }
;             rstd[rr] = 1.0f / sqrtf(wave_sum(ss) * (1.0f / D) + EPS); }
; #pragma unroll
;         for (int j = 0; j < 8; ++j) { const f32x4 g = ((const f32x4*)gpost)[lane + 64 * j];
; #pragma unroll
;             for (int rr = 0; rr < NR; ++rr) { v[rr][j] = v[rr][j] + bf4(mr[rr][j]) * rstd[rr] * g;
;                 if (DST16) { v2u w; w.x = pk2(v[rr][j].x, v[rr][j].y); w.y = pk2(v[rr][j].z, v[rr][j].w); ((v2u*)((bf16*)xdst + rr * rstride))[lane + 64 * j] = w; }
;                 else __builtin_nontemporal_store(v[rr][j], (f32x4*)((float*)xdst + rr * rstride) + lane + 64 * j); } }
;     }
;     if (WRITE_H) {
; #pragma unroll
;         for (int rr = 0; rr < NR; ++rr) { float ss = 0.f;
; #pragma unroll
;             for (int j = 0; j < 8; ++j) ss += (v[rr][j].x * v[rr][j].x + v[rr][j].y * v[rr][j].y) + (v[rr][j].z * v[rr][j].z + v[rr][j].w * v[rr][j].w);
;             const float rstd = 1.0f / sqrtf(wave_sum(ss) * (1.0f / D) + EPS);
;             if (lane == 0) rsd[rr * rsstride] = rstd; }
.Lr0_last:
	s_waitcnt vmcnt(13)
	v_mov_b32_e32 v136, 0
	v_mov_b32_e32 v137, 0
	v_mov_b32_e32 v138, 0
	v_mov_b32_e32 v139, 0
	s_lshl_b32 s26, s20, 12
	v_add_u32_e32 v134, s26, v131
	v_fmac_f32_e32 v136, v32, v32
	v_fmac_f32_e32 v137, v33, v33
	v_fmac_f32_e32 v138, v34, v34
	v_fmac_f32_e32 v139, v35, v35
	v_fmac_f32_e32 v136, v36, v36
	v_fmac_f32_e32 v137, v37, v37
	v_fmac_f32_e32 v138, v38, v38
	v_fmac_f32_e32 v139, v39, v39
	v_cvt_pk_bf16_f32 v32, v32, v33
	v_cvt_pk_bf16_f32 v33, v34, v35
	v_cvt_pk_bf16_f32 v34, v36, v37
	v_cvt_pk_bf16_f32 v35, v38, v39
	global_store_dwordx4 v134, v[32:35], s[2:3]
	v_fmac_f32_e32 v136, v40, v40
	v_fmac_f32_e32 v137, v41, v41
	v_fmac_f32_e32 v138, v42, v42
	v_fmac_f32_e32 v139, v43, v43
	v_fmac_f32_e32 v136, v44, v44
	v_fmac_f32_e32 v137, v45, v45
	v_fmac_f32_e32 v138, v46, v46
	v_fmac_f32_e32 v139, v47, v47
	v_cvt_pk_bf16_f32 v40, v40, v41
	v_cvt_pk_bf16_f32 v41, v42, v43
	v_cvt_pk_bf16_f32 v42, v44, v45
	v_cvt_pk_bf16_f32 v43, v46, v47
	global_store_dwordx4 v134, v[40:43], s[2:3] offset:1024
	v_fmac_f32_e32 v136, v48, v48
	v_fmac_f32_e32 v137, v49, v49
	v_fmac_f32_e32 v138, v50, v50
	v_fmac_f32_e32 v139, v51, v51
	v_fmac_f32_e32 v136, v52, v52
	v_fmac_f32_e32 v137, v53, v53
	v_fmac_f32_e32 v138, v54, v54
	v_fmac_f32_e32 v139, v55, v55
	v_cvt_pk_bf16_f32 v48, v48, v49
	v_cvt_pk_bf16_f32 v49, v50, v51
	v_cvt_pk_bf16_f32 v50, v52, v53
	v_cvt_pk_bf16_f32 v51, v54, v55
	global_store_dwordx4 v134, v[48:51], s[2:3] offset:2048
	v_fmac_f32_e32 v136, v56, v56
	v_fmac_f32_e32 v137, v57, v57
	v_fmac_f32_e32 v138, v58, v58
	v_fmac_f32_e32 v139, v59, v59
	v_fmac_f32_e32 v136, v60, v60
	v_fmac_f32_e32 v137, v61, v61
	v_fmac_f32_e32 v138, v62, v62
	v_fmac_f32_e32 v139, v63, v63
	v_cvt_pk_bf16_f32 v56, v56, v57
	v_cvt_pk_bf16_f32 v57, v58, v59
	v_cvt_pk_bf16_f32 v58, v60, v61
	v_cvt_pk_bf16_f32 v59, v62, v63
	global_store_dwordx4 v134, v[56:59], s[2:3] offset:3072
	v_add_f32_e32 v136, v136, v137
	v_add_f32_e32 v138, v138, v139
	v_add_f32_e32 v136, v136, v138
	s_nop 1
	v_add_f32_dpp v136, v136, v136 quad_perm:[1,0,3,2] row_mask:0xf bank_mask:0xf
	s_nop 1
	v_add_f32_dpp v136, v136, v136 quad_perm:[2,3,0,1] row_mask:0xf bank_mask:0xf
	s_nop 1
	v_add_f32_dpp v136, v136, v136 row_half_mirror row_mask:0xf bank_mask:0xf
	s_nop 1
	v_add_f32_dpp v136, v136, v136 row_mirror row_mask:0xf bank_mask:0xf
	s_nop 1
	v_readlane_b32 s16, v136, 0
	v_readlane_b32 s17, v136, 16
	v_readlane_b32 s18, v136, 32
	v_readlane_b32 s19, v136, 48
	s_nop 1
	v_mov_b32_e32 v137, s16
	v_add_f32_e32 v137, s17, v137
	v_add_f32_e32 v137, s18, v137
	v_add_f32_e32 v137, s19, v137
	v_mov_b32_e32 v138, s25
	v_fma_f32 v137, v137, s24, v138
	v_rsq_f32_e32 v128, v137
	v_mul_f32_e32 v137, 0.5, v137
	v_mul_f32_e32 v138, v137, v128
	v_fma_f32 v138, -v138, v128, 0.5
	v_fma_f32 v128, v128, v138, v128
	s_lshl_b32 s26, s20, 2
	s_add_u32 s26, s4, s26
	s_addc_u32 s27, s5, 0
	v_mov_b32_e32 v139, 0
	s_mov_b64 exec, 1
	global_store_dword v139, v128, s[26:27]
	s_mov_b64 exec, -1
	s_waitcnt vmcnt(5)
	v_mov_b32_e32 v136, 0
	v_mov_b32_e32 v137, 0
	v_mov_b32_e32 v138, 0
	v_mov_b32_e32 v139, 0
	s_lshl_b32 s26, s22, 12
	v_add_u32_e32 v135, s26, v131
	v_fmac_f32_e32 v136, v64, v64
	v_fmac_f32_e32 v137, v65, v65
	v_fmac_f32_e32 v138, v66, v66
	v_fmac_f32_e32 v139, v67, v67
	v_fmac_f32_e32 v136, v68, v68
	v_fmac_f32_e32 v137, v69, v69
	v_fmac_f32_e32 v138, v70, v70
	v_fmac_f32_e32 v139, v71, v71
	v_cvt_pk_bf16_f32 v64, v64, v65
	v_cvt_pk_bf16_f32 v65, v66, v67
	v_cvt_pk_bf16_f32 v66, v68, v69
	v_cvt_pk_bf16_f32 v67, v70, v71
	global_store_dwordx4 v135, v[64:67], s[2:3]
	v_fmac_f32_e32 v136, v72, v72
	v_fmac_f32_e32 v137, v73, v73
	v_fmac_f32_e32 v138, v74, v74
	v_fmac_f32_e32 v139, v75, v75
	v_fmac_f32_e32 v136, v76, v76
	v_fmac_f32_e32 v137, v77, v77
	v_fmac_f32_e32 v138, v78, v78
	v_fmac_f32_e32 v139, v79, v79
	v_cvt_pk_bf16_f32 v72, v72, v73
	v_cvt_pk_bf16_f32 v73, v74, v75
	v_cvt_pk_bf16_f32 v74, v76, v77
	v_cvt_pk_bf16_f32 v75, v78, v79
	global_store_dwordx4 v135, v[72:75], s[2:3] offset:1024
	v_fmac_f32_e32 v136, v80, v80
	v_fmac_f32_e32 v137, v81, v81
	v_fmac_f32_e32 v138, v82, v82
	v_fmac_f32_e32 v139, v83, v83
	v_fmac_f32_e32 v136, v84, v84
	v_fmac_f32_e32 v137, v85, v85
	v_fmac_f32_e32 v138, v86, v86
	v_fmac_f32_e32 v139, v87, v87
	v_cvt_pk_bf16_f32 v80, v80, v81
	v_cvt_pk_bf16_f32 v81, v82, v83
	v_cvt_pk_bf16_f32 v82, v84, v85
	v_cvt_pk_bf16_f32 v83, v86, v87
	global_store_dwordx4 v135, v[80:83], s[2:3] offset:2048
	v_fmac_f32_e32 v136, v88, v88
	v_fmac_f32_e32 v137, v89, v89
	v_fmac_f32_e32 v138, v90, v90
	v_fmac_f32_e32 v139, v91, v91
	v_fmac_f32_e32 v136, v92, v92
	v_fmac_f32_e32 v137, v93, v93
	v_fmac_f32_e32 v138, v94, v94
	v_fmac_f32_e32 v139, v95, v95
	v_cvt_pk_bf16_f32 v88, v88, v89
	v_cvt_pk_bf16_f32 v89, v90, v91
	v_cvt_pk_bf16_f32 v90, v92, v93
	v_cvt_pk_bf16_f32 v91, v94, v95
	global_store_dwordx4 v135, v[88:91], s[2:3] offset:3072
	v_add_f32_e32 v136, v136, v137
	v_add_f32_e32 v138, v138, v139
	v_add_f32_e32 v136, v136, v138
	s_nop 1
	v_add_f32_dpp v136, v136, v136 quad_perm:[1,0,3,2] row_mask:0xf bank_mask:0xf
	s_nop 1
	v_add_f32_dpp v136, v136, v136 quad_perm:[2,3,0,1] row_mask:0xf bank_mask:0xf
	s_nop 1
	v_add_f32_dpp v136, v136, v136 row_half_mirror row_mask:0xf bank_mask:0xf
	s_nop 1
	v_add_f32_dpp v136, v136, v136 row_mirror row_mask:0xf bank_mask:0xf
	s_nop 1
	v_readlane_b32 s16, v136, 0
	v_readlane_b32 s17, v136, 16
	v_readlane_b32 s18, v136, 32
	v_readlane_b32 s19, v136, 48
	s_nop 1
	v_mov_b32_e32 v137, s16
	v_add_f32_e32 v137, s17, v137
	v_add_f32_e32 v137, s18, v137
	v_add_f32_e32 v137, s19, v137
	v_mov_b32_e32 v138, s25
	v_fma_f32 v137, v137, s24, v138
	v_rsq_f32_e32 v128, v137
	v_mul_f32_e32 v137, 0.5, v137
	v_mul_f32_e32 v138, v137, v128
	v_fma_f32 v138, -v138, v128, 0.5
	v_fma_f32 v128, v128, v138, v128
	s_lshl_b32 s26, s22, 2
	s_add_u32 s26, s4, s26
	s_addc_u32 s27, s5, 0
	v_mov_b32_e32 v139, 0
	s_mov_b64 exec, 1
	global_store_dword v139, v128, s[26:27]
	s_mov_b64 exec, -1
.Lr0_done:
.LBB0_216:
	s_mov_b64 s[16:17], 0

; #define PG8_STAGE(bufoff, gbase, voff) do { _Pragma("unroll") for (int _i = 0; _i < 2; ++_i) \
;         __builtin_amdgcn_global_load_lds((const unsigned*)((const char*)(gbase) + (voff)[_i]), (PG8_LAS unsigned*)(lds + (bufoff) + ldsw + _i * 8192), 16, 0, 0); } while (0)
; #define PG8_LDA(dst, b, h) do { _Pragma("unroll") for (int m = 0; m < 4; ++m) _Pragma("unroll") for (int k = 0; k < 2; ++k) dst[m][k] = *(const PG8_LAS bf16x8*)(lds + PG8_SA(b, h) + aoff + m * 2048 + k * 1024); } while (0)
; #define PG8_LDB(dst, b, h) do { _Pragma("unroll") for (int n = 0; n < 2; ++n) _Pragma("unroll") for (int k = 0; k < 2; ++k) dst[n][k] = *(const PG8_LAS bf16x8*)(lds + PG8_SB(b, h) + boff + n * 2048 + k * 1024); } while (0)
; #define PG8_MMA(ai, bj, At, Bt) do { __builtin_amdgcn_s_setprio(1); _Pragma("unroll") for (int m = 0; m < 4; ++m) _Pragma("unroll") for (int n = 0; n < 2; ++n) _Pragma("unroll") for (int k = 0; k < 2; ++k) \
;         acc[ai][bj][m][n] = __builtin_amdgcn_mfma_f32_16x16x32_bf16(Bt[n][k], At[m][k], acc[ai][bj][m][n], 0, 0, 0); __builtin_amdgcn_s_setprio(0); } while (0)
; #define PG8_WAIT_V(n) asm volatile("s_waitcnt vmcnt(" #n ")" ::: "memory")
; #define PG8_WAIT_L(n) asm volatile("s_waitcnt lgkmcnt(" #n ")" ::: "memory")
; #define PG8_BAR __builtin_amdgcn_s_barrier()
; #define PG8_SCHED __builtin_amdgcn_sched_barrier(0)
; template <class Epi, class Sched, bool ALIGN_EPI = false, bool SP2 = false>
; __device__ __forceinline__ void gemm_phase(PG8_LAS unsigned char* lds, const Gemm g, const Sched& S, const Epi& E) {
;     ...
;             PG8_LDB(B0, 0, 0); PG8_LDB(B1, 0, 1); PG8_SCHED; PG8_LDA(At, 0, 0); PG8_STAGE(PG8_SA(1, 1), a1 + hstep, voffA);
;             PG8_WAIT_V(8); PG8_WAIT_L(0); PG8_BAR; PG8_MMA(0, 0, At, B0); PG8_MMA(0, 1, At, B1); PG8_BAR; PG8_SCHED;
;             PG8_LDA(At, 0, 1); PG8_STAGE(PG8_SB(0, 0), b2, voffB); PG8_STAGE(PG8_SB(0, 1), b2 + hstep, voffB); PG8_STAGE(PG8_SA(0, 0), a2, voffA);
;             PG8_WAIT_V(8); PG8_WAIT_L(0); PG8_BAR; PG8_MMA(1, 0, At, B0); PG8_MMA(1, 1, At, B1); PG8_BAR; PG8_SCHED;
;     ...
;         for (int a = 0; a < 2; ++a)
; #pragma unroll
;             for (int b = 0; b < 2; ++b)
; #pragma unroll
;                 for (int m = 0; m < 4; ++m)
; #pragma unroll
;                     for (int n = 0; n < 2; ++n) acc[a][b][m][n] = (f32x4){0.f, 0.f, 0.f, 0.f};
.LBB0_299:
	s_add_u32 vcc_lo, s8, 0x100
	s_addc_u32 vcc_hi, s9, 0
	s_add_u32 s6, s82, 0x80
	s_addc_u32 s7, s83, 0
	s_mov_b32 s8, 0
	s_cmp_eq_u32 s93, 1
	s_cbranch_scc0 .Lk_peel_b
	s_add_i32 s82, s8, 2
	s_add_u32 s46, s6, 0x80
	s_addc_u32 s9, s7, 0
	s_cmp_eq_u32 s96, s8
	s_cselect_b32 s9, s79, s9
	s_cselect_b32 s8, s78, s46
	s_cselect_b32 s47, s81, vcc_hi
	s_cselect_b32 s46, s80, vcc_lo
	ds_read_b128 v[142:145], v232
	ds_read_b128 v[146:149], v232 offset:1024
	ds_read_b128 v[174:177], v232 offset:2048
	ds_read_b128 v[178:181], v232 offset:3072
	ds_read_b128 v[182:185], v232 offset:16384
	ds_read_b128 v[186:189], v232 offset:17408
	ds_read_b128 v[190:193], v232 offset:18432
	ds_read_b128 v[194:197], v232 offset:19456
	s_add_i32 m0, s68, 0xc000
	ds_read_b128 v[198:201], v173
	ds_read_b128 v[202:205], v173 offset:1024
	ds_read_b128 v[206:209], v173 offset:2048
	ds_read_b128 v[210:213], v173 offset:3072
	ds_read_b128 v[214:217], v173 offset:4096
	ds_read_b128 v[218:221], v173 offset:5120
	ds_read_b128 v[222:225], v173 offset:6144
	ds_read_b128 v[226:229], v173 offset:7168
	global_load_lds_dwordx4 v140, s[6:7]
	s_add_i32 m0, s68, 0xe000
	s_nop 0
	global_load_lds_dwordx4 v138, s[6:7]
	s_waitcnt vmcnt(8)
	s_waitcnt lgkmcnt(0)
	s_barrier
	s_setprio 1
	v_mfma_f32_16x16x32_bf16 v[124:127], v[142:145], v[198:201], 0
	v_mfma_f32_16x16x32_bf16 v[120:123], v[174:177], v[198:201], 0
	v_mfma_f32_16x16x32_bf16 v[108:111], v[142:145], v[206:209], 0
	v_mfma_f32_16x16x32_bf16 v[104:107], v[174:177], v[206:209], 0
	v_mfma_f32_16x16x32_bf16 v[92:95], v[142:145], v[214:217], 0
	v_mfma_f32_16x16x32_bf16 v[88:91], v[174:177], v[214:217], 0
	v_mfma_f32_16x16x32_bf16 v[76:79], v[142:145], v[222:225], 0
	v_mfma_f32_16x16x32_bf16 v[72:75], v[174:177], v[222:225], 0
	v_mfma_f32_16x16x32_bf16 v[124:127], v[146:149], v[202:205], v[124:127]
	v_mfma_f32_16x16x32_bf16 v[120:123], v[178:181], v[202:205], v[120:123]
	v_mfma_f32_16x16x32_bf16 v[108:111], v[146:149], v[210:213], v[108:111]
	v_mfma_f32_16x16x32_bf16 v[104:107], v[178:181], v[210:213], v[104:107]
	v_mfma_f32_16x16x32_bf16 v[92:95], v[146:149], v[218:221], v[92:95]
	v_mfma_f32_16x16x32_bf16 v[88:91], v[178:181], v[218:221], v[88:91]
	v_mfma_f32_16x16x32_bf16 v[76:79], v[146:149], v[226:229], v[76:79]
	v_mfma_f32_16x16x32_bf16 v[72:75], v[178:181], v[226:229], v[72:75]
	s_setprio 0
	s_setprio 1
	v_mfma_f32_16x16x32_bf16 v[116:119], v[182:185], v[198:201], 0
	v_mfma_f32_16x16x32_bf16 v[112:115], v[190:193], v[198:201], 0
	v_mfma_f32_16x16x32_bf16 v[100:103], v[182:185], v[206:209], 0
	v_mfma_f32_16x16x32_bf16 v[96:99], v[190:193], v[206:209], 0
	v_mfma_f32_16x16x32_bf16 v[84:87], v[182:185], v[214:217], 0
	v_mfma_f32_16x16x32_bf16 v[80:83], v[190:193], v[214:217], 0
	v_mfma_f32_16x16x32_bf16 v[68:71], v[182:185], v[222:225], 0
	v_mfma_f32_16x16x32_bf16 v[64:67], v[190:193], v[222:225], 0
	v_mfma_f32_16x16x32_bf16 v[116:119], v[186:189], v[202:205], v[116:119]
	v_mfma_f32_16x16x32_bf16 v[112:115], v[194:197], v[202:205], v[112:115]
	v_mfma_f32_16x16x32_bf16 v[100:103], v[186:189], v[210:213], v[100:103]
	v_mfma_f32_16x16x32_bf16 v[96:99], v[194:197], v[210:213], v[96:99]
	v_mfma_f32_16x16x32_bf16 v[84:87], v[186:189], v[218:221], v[84:87]
	v_mfma_f32_16x16x32_bf16 v[80:83], v[194:197], v[218:221], v[80:83]
	v_mfma_f32_16x16x32_bf16 v[68:71], v[186:189], v[226:229], v[68:71]
	v_mfma_f32_16x16x32_bf16 v[64:67], v[194:197], v[226:229], v[64:67]
	s_setprio 0
	s_barrier
	s_add_i32 m0, s65, 0x10000
	ds_read_b128 v[198:201], v173 offset:16384
	ds_read_b128 v[202:205], v173 offset:17408
	ds_read_b128 v[206:209], v173 offset:18432
	ds_read_b128 v[210:213], v173 offset:19456
	ds_read_b128 v[214:217], v173 offset:20480
	ds_read_b128 v[218:221], v173 offset:21504
	ds_read_b128 v[222:225], v173 offset:22528
	ds_read_b128 v[226:229], v173 offset:23552
	global_load_lds_dwordx4 v128, s[46:47]
	s_add_i32 m0, s65, 0x12000
	s_nop 0
	global_load_lds_dwordx4 v136, s[46:47]
	s_add_i32 m0, s65, 0x14000
	s_nop 0
	global_load_lds_dwordx4 v230, s[46:47]
	s_add_i32 m0, s65, 0x16000
	s_nop 0
	global_load_lds_dwordx4 v231, s[46:47]
	s_mov_b32 m0, s68
	s_nop 0
	global_load_lds_dwordx4 v132, s[8:9]
	s_mov_b32 m0, s87
	s_nop 0
	global_load_lds_dwordx4 v134, s[8:9]
	s_waitcnt vmcnt(8)
	s_waitcnt lgkmcnt(0)
	s_barrier
	s_setprio 1
	v_mfma_f32_16x16x32_bf16 v[60:63], v[142:145], v[198:201], 0
	v_mfma_f32_16x16x32_bf16 v[56:59], v[174:177], v[198:201], 0
	v_mfma_f32_16x16x32_bf16 v[44:47], v[142:145], v[206:209], 0
	v_mfma_f32_16x16x32_bf16 v[40:43], v[174:177], v[206:209], 0
	v_mfma_f32_16x16x32_bf16 v[28:31], v[142:145], v[214:217], 0
	v_mfma_f32_16x16x32_bf16 v[24:27], v[174:177], v[214:217], 0
	v_mfma_f32_16x16x32_bf16 v[12:15], v[142:145], v[222:225], 0
	v_mfma_f32_16x16x32_bf16 v[8:11], v[174:177], v[222:225], 0
	v_mfma_f32_16x16x32_bf16 v[60:63], v[146:149], v[202:205], v[60:63]
	v_mfma_f32_16x16x32_bf16 v[56:59], v[178:181], v[202:205], v[56:59]
	v_mfma_f32_16x16x32_bf16 v[44:47], v[146:149], v[210:213], v[44:47]
	v_mfma_f32_16x16x32_bf16 v[40:43], v[178:181], v[210:213], v[40:43]
	v_mfma_f32_16x16x32_bf16 v[28:31], v[146:149], v[218:221], v[28:31]
	v_mfma_f32_16x16x32_bf16 v[24:27], v[178:181], v[218:221], v[24:27]
	v_mfma_f32_16x16x32_bf16 v[12:15], v[146:149], v[226:229], v[12:15]
	v_mfma_f32_16x16x32_bf16 v[8:11], v[178:181], v[226:229], v[8:11]
	s_setprio 0
	s_setprio 1
	v_mfma_f32_16x16x32_bf16 v[52:55], v[182:185], v[198:201], 0
	v_mfma_f32_16x16x32_bf16 v[48:51], v[190:193], v[198:201], 0
	v_mfma_f32_16x16x32_bf16 v[36:39], v[182:185], v[206:209], 0
	v_mfma_f32_16x16x32_bf16 v[32:35], v[190:193], v[206:209], 0
	v_mfma_f32_16x16x32_bf16 v[20:23], v[182:185], v[214:217], 0
	v_mfma_f32_16x16x32_bf16 v[16:19], v[190:193], v[214:217], 0
	v_mfma_f32_16x16x32_bf16 v[4:7], v[182:185], v[222:225], 0
	v_mfma_f32_16x16x32_bf16 v[0:3], v[190:193], v[222:225], 0
	v_mfma_f32_16x16x32_bf16 v[52:55], v[186:189], v[202:205], v[52:55]
	v_mfma_f32_16x16x32_bf16 v[48:51], v[194:197], v[202:205], v[48:51]
	v_mfma_f32_16x16x32_bf16 v[36:39], v[186:189], v[210:213], v[36:39]
	v_mfma_f32_16x16x32_bf16 v[32:35], v[194:197], v[210:213], v[32:35]
	v_mfma_f32_16x16x32_bf16 v[20:23], v[186:189], v[218:221], v[20:23]
	v_mfma_f32_16x16x32_bf16 v[16:19], v[194:197], v[218:221], v[16:19]
	v_mfma_f32_16x16x32_bf16 v[4:7], v[186:189], v[226:229], v[4:7]
	v_mfma_f32_16x16x32_bf16 v[0:3], v[194:197], v[226:229], v[0:3]
	s_setprio 0
	s_barrier
; #define PG8_STAGE(bufoff, gbase, voff) do { _Pragma("unroll") for (int _i = 0; _i < 2; ++_i) \
;         __builtin_amdgcn_global_load_lds((const unsigned*)((const char*)(gbase) + (voff)[_i]), (PG8_LAS unsigned*)(lds + (bufoff) + ldsw + _i * 8192), 16, 0, 0); } while (0)
; #define PG8_LDA(dst, b, h) do { _Pragma("unroll") for (int m = 0; m < 4; ++m) _Pragma("unroll") for (int k = 0; k < 2; ++k) dst[m][k] = *(const PG8_LAS bf16x8*)(lds + PG8_SA(b, h) + aoff + m * 2048 + k * 1024); } while (0)
; #define PG8_LDB(dst, b, h) do { _Pragma("unroll") for (int n = 0; n < 2; ++n) _Pragma("unroll") for (int k = 0; k < 2; ++k) dst[n][k] = *(const PG8_LAS bf16x8*)(lds + PG8_SB(b, h) + boff + n * 2048 + k * 1024); } while (0)
; #define PG8_MMA(ai, bj, At, Bt) do { __builtin_amdgcn_s_setprio(1); _Pragma("unroll") for (int m = 0; m < 4; ++m) _Pragma("unroll") for (int n = 0; n < 2; ++n) _Pragma("unroll") for (int k = 0; k < 2; ++k) \
;         acc[ai][bj][m][n] = __builtin_amdgcn_mfma_f32_16x16x32_bf16(Bt[n][k], At[m][k], acc[ai][bj][m][n], 0, 0, 0); __builtin_amdgcn_s_setprio(0); } while (0)
; #define PG8_WAIT_V(n) asm volatile("s_waitcnt vmcnt(" #n ")" ::: "memory")
; #define PG8_WAIT_L(n) asm volatile("s_waitcnt lgkmcnt(" #n ")" ::: "memory")
; #define PG8_BAR __builtin_amdgcn_s_barrier()
; #define PG8_SCHED __builtin_amdgcn_sched_barrier(0)
; template <class Epi, class Sched, bool ALIGN_EPI = false, bool SP2 = false>
; __device__ __forceinline__ void gemm_phase(PG8_LAS unsigned char* lds, const Gemm g, const Sched& S, const Epi& E) {
;     ...
;         for (int t = 0; t < nt; t += 2) {
;     ...
;             PG8_LDB(B0, 1, 0); PG8_LDB(B1, 1, 1); PG8_SCHED; PG8_LDA(At, 1, 0); PG8_STAGE(PG8_SA(0, 1), a2 + hstep, voffA);
;             PG8_WAIT_V(8); PG8_WAIT_L(0); PG8_BAR; PG8_MMA(0, 0, At, B0); PG8_MMA(0, 1, At, B1); PG8_BAR; PG8_SCHED;
;             PG8_LDA(At, 1, 1); PG8_STAGE(PG8_SB(1, 0), b3, voffB); PG8_STAGE(PG8_SB(1, 1), b3 + hstep, voffB); PG8_STAGE(PG8_SA(1, 0), a3, voffA);
;             PG8_WAIT_V(8); PG8_WAIT_L(0); PG8_BAR; PG8_MMA(1, 0, At, B0); PG8_MMA(1, 1, At, B1); PG8_BAR; PG8_SCHED;
	ds_read_b128 v[142:145], v232 offset:32768
	ds_read_b128 v[146:149], v232 offset:33792
	ds_read_b128 v[174:177], v232 offset:34816
	ds_read_b128 v[178:181], v232 offset:35840
	ds_read_b128 v[182:185], v232 offset:49152
	ds_read_b128 v[186:189], v232 offset:50176
	ds_read_b128 v[190:193], v232 offset:51200
	ds_read_b128 v[194:197], v232 offset:52224
	s_mov_b32 m0, s1
	ds_read_b128 v[198:201], v173 offset:32768
	ds_read_b128 v[202:205], v173 offset:33792
	ds_read_b128 v[206:209], v173 offset:34816
	ds_read_b128 v[210:213], v173 offset:35840
	ds_read_b128 v[214:217], v173 offset:36864
	ds_read_b128 v[218:221], v173 offset:37888
	ds_read_b128 v[222:225], v173 offset:38912
	ds_read_b128 v[226:229], v173 offset:39936
	global_load_lds_dwordx4 v140, s[8:9]
	s_mov_b32 m0, s0
	s_nop 0
	global_load_lds_dwordx4 v138, s[8:9]
	s_waitcnt vmcnt(8)
	s_waitcnt lgkmcnt(0)
	s_barrier
	s_setprio 1
	v_mfma_f32_16x16x32_bf16 v[124:127], v[142:145], v[198:201], v[124:127]
	v_mfma_f32_16x16x32_bf16 v[120:123], v[174:177], v[198:201], v[120:123]
	v_mfma_f32_16x16x32_bf16 v[108:111], v[142:145], v[206:209], v[108:111]
	v_mfma_f32_16x16x32_bf16 v[104:107], v[174:177], v[206:209], v[104:107]
	v_mfma_f32_16x16x32_bf16 v[92:95], v[142:145], v[214:217], v[92:95]
	v_mfma_f32_16x16x32_bf16 v[88:91], v[174:177], v[214:217], v[88:91]
	v_mfma_f32_16x16x32_bf16 v[76:79], v[142:145], v[222:225], v[76:79]
	v_mfma_f32_16x16x32_bf16 v[72:75], v[174:177], v[222:225], v[72:75]
	v_mfma_f32_16x16x32_bf16 v[124:127], v[146:149], v[202:205], v[124:127]
	v_mfma_f32_16x16x32_bf16 v[120:123], v[178:181], v[202:205], v[120:123]
	v_mfma_f32_16x16x32_bf16 v[108:111], v[146:149], v[210:213], v[108:111]
	v_mfma_f32_16x16x32_bf16 v[104:107], v[178:181], v[210:213], v[104:107]
	v_mfma_f32_16x16x32_bf16 v[92:95], v[146:149], v[218:221], v[92:95]
	v_mfma_f32_16x16x32_bf16 v[88:91], v[178:181], v[218:221], v[88:91]
	v_mfma_f32_16x16x32_bf16 v[76:79], v[146:149], v[226:229], v[76:79]
	v_mfma_f32_16x16x32_bf16 v[72:75], v[178:181], v[226:229], v[72:75]
	s_setprio 0
	s_setprio 1
	v_mfma_f32_16x16x32_bf16 v[116:119], v[182:185], v[198:201], v[116:119]
	v_mfma_f32_16x16x32_bf16 v[112:115], v[190:193], v[198:201], v[112:115]
	v_mfma_f32_16x16x32_bf16 v[100:103], v[182:185], v[206:209], v[100:103]
	v_mfma_f32_16x16x32_bf16 v[96:99], v[190:193], v[206:209], v[96:99]
	v_mfma_f32_16x16x32_bf16 v[84:87], v[182:185], v[214:217], v[84:87]
	v_mfma_f32_16x16x32_bf16 v[80:83], v[190:193], v[214:217], v[80:83]
	v_mfma_f32_16x16x32_bf16 v[68:71], v[182:185], v[222:225], v[68:71]
	v_mfma_f32_16x16x32_bf16 v[64:67], v[190:193], v[222:225], v[64:67]
	v_mfma_f32_16x16x32_bf16 v[116:119], v[186:189], v[202:205], v[116:119]
	v_mfma_f32_16x16x32_bf16 v[112:115], v[194:197], v[202:205], v[112:115]
	v_mfma_f32_16x16x32_bf16 v[100:103], v[186:189], v[210:213], v[100:103]
	v_mfma_f32_16x16x32_bf16 v[96:99], v[194:197], v[210:213], v[96:99]
	v_mfma_f32_16x16x32_bf16 v[84:87], v[186:189], v[218:221], v[84:87]
	v_mfma_f32_16x16x32_bf16 v[80:83], v[194:197], v[218:221], v[80:83]
	v_mfma_f32_16x16x32_bf16 v[68:71], v[186:189], v[226:229], v[68:71]
	v_mfma_f32_16x16x32_bf16 v[64:67], v[194:197], v[226:229], v[64:67]
	s_setprio 0
	s_barrier
	s_add_i32 m0, s65, 0x17f80
	ds_read_b128 v[198:201], v173 offset:49152
	ds_read_b128 v[202:205], v173 offset:50176
	ds_read_b128 v[206:209], v173 offset:51200
	ds_read_b128 v[210:213], v173 offset:52224
	ds_read_b128 v[214:217], v173 offset:53248
	ds_read_b128 v[218:221], v173 offset:54272
	ds_read_b128 v[222:225], v173 offset:55296
	ds_read_b128 v[226:229], v173 offset:56320
	global_load_lds_dwordx4 v128, s[46:47] offset:128
	s_add_i32 m0, s65, 0x19f80
	s_nop 0
	global_load_lds_dwordx4 v136, s[46:47] offset:128
	s_add_i32 m0, s65, 0x1bf80
	s_nop 0
	global_load_lds_dwordx4 v230, s[46:47] offset:128
	s_add_i32 m0, s65, 0x1df80
	s_nop 0
	global_load_lds_dwordx4 v231, s[46:47] offset:128
	s_add_i32 m0, s88, 0xffffff80
	s_nop 0
	global_load_lds_dwordx4 v132, s[8:9] offset:128
	s_add_i32 m0, s95, 0xffffff80
	s_nop 0
	global_load_lds_dwordx4 v134, s[8:9] offset:128
	s_waitcnt vmcnt(8)
	s_waitcnt lgkmcnt(0)
	s_barrier
	s_setprio 1
	v_mfma_f32_16x16x32_bf16 v[60:63], v[142:145], v[198:201], v[60:63]
	v_mfma_f32_16x16x32_bf16 v[56:59], v[174:177], v[198:201], v[56:59]
	v_mfma_f32_16x16x32_bf16 v[44:47], v[142:145], v[206:209], v[44:47]
	v_mfma_f32_16x16x32_bf16 v[40:43], v[174:177], v[206:209], v[40:43]
	v_mfma_f32_16x16x32_bf16 v[28:31], v[142:145], v[214:217], v[28:31]
	v_mfma_f32_16x16x32_bf16 v[24:27], v[174:177], v[214:217], v[24:27]
	v_mfma_f32_16x16x32_bf16 v[12:15], v[142:145], v[222:225], v[12:15]
	v_mfma_f32_16x16x32_bf16 v[8:11], v[174:177], v[222:225], v[8:11]
	v_mfma_f32_16x16x32_bf16 v[60:63], v[146:149], v[202:205], v[60:63]
	v_mfma_f32_16x16x32_bf16 v[56:59], v[178:181], v[202:205], v[56:59]
	v_mfma_f32_16x16x32_bf16 v[44:47], v[146:149], v[210:213], v[44:47]
	v_mfma_f32_16x16x32_bf16 v[40:43], v[178:181], v[210:213], v[40:43]
	v_mfma_f32_16x16x32_bf16 v[28:31], v[146:149], v[218:221], v[28:31]
	v_mfma_f32_16x16x32_bf16 v[24:27], v[178:181], v[218:221], v[24:27]
	v_mfma_f32_16x16x32_bf16 v[12:15], v[146:149], v[226:229], v[12:15]
	v_mfma_f32_16x16x32_bf16 v[8:11], v[178:181], v[226:229], v[8:11]
	s_setprio 0
	s_setprio 1
	v_mfma_f32_16x16x32_bf16 v[52:55], v[182:185], v[198:201], v[52:55]
	v_mfma_f32_16x16x32_bf16 v[48:51], v[190:193], v[198:201], v[48:51]
	v_mfma_f32_16x16x32_bf16 v[36:39], v[182:185], v[206:209], v[36:39]
	v_mfma_f32_16x16x32_bf16 v[32:35], v[190:193], v[206:209], v[32:35]
	v_mfma_f32_16x16x32_bf16 v[20:23], v[182:185], v[214:217], v[20:23]
	v_mfma_f32_16x16x32_bf16 v[16:19], v[190:193], v[214:217], v[16:19]
	v_mfma_f32_16x16x32_bf16 v[4:7], v[182:185], v[222:225], v[4:7]
	v_mfma_f32_16x16x32_bf16 v[0:3], v[190:193], v[222:225], v[0:3]
	v_mfma_f32_16x16x32_bf16 v[52:55], v[186:189], v[202:205], v[52:55]
	v_mfma_f32_16x16x32_bf16 v[48:51], v[194:197], v[202:205], v[48:51]
	v_mfma_f32_16x16x32_bf16 v[36:39], v[186:189], v[210:213], v[36:39]
	v_mfma_f32_16x16x32_bf16 v[32:35], v[194:197], v[210:213], v[32:35]
	v_mfma_f32_16x16x32_bf16 v[20:23], v[186:189], v[218:221], v[20:23]
	v_mfma_f32_16x16x32_bf16 v[16:19], v[194:197], v[218:221], v[16:19]
	v_mfma_f32_16x16x32_bf16 v[4:7], v[186:189], v[226:229], v[4:7]
	v_mfma_f32_16x16x32_bf16 v[0:3], v[194:197], v[226:229], v[0:3]
	s_setprio 0
	s_barrier
	s_add_u32 vcc_lo, vcc_lo, 0x100
	s_addc_u32 vcc_hi, vcc_hi, 0
	s_add_u32 s6, s6, 0x100
	s_addc_u32 s7, s7, 0
	s_cmp_ge_u32 s82, s97
	s_mov_b32 s8, s82
	s_cbranch_scc1 .Lk_done
	s_branch .LBB0_300
; #define PG8_STAGE(bufoff, gbase, voff) do { _Pragma("unroll") for (int _i = 0; _i < 2; ++_i) \
;         __builtin_amdgcn_global_load_lds((const unsigned*)((const char*)(gbase) + (voff)[_i]), (PG8_LAS unsigned*)(lds + (bufoff) + ldsw + _i * 8192), 16, 0, 0); } while (0)
; #define PG8_LDA(dst, b, h) do { _Pragma("unroll") for (int m = 0; m < 4; ++m) _Pragma("unroll") for (int k = 0; k < 2; ++k) dst[m][k] = *(const PG8_LAS bf16x8*)(lds + PG8_SA(b, h) + aoff + m * 2048 + k * 1024); } while (0)
; #define PG8_LDB(dst, b, h) do { _Pragma("unroll") for (int n = 0; n < 2; ++n) _Pragma("unroll") for (int k = 0; k < 2; ++k) dst[n][k] = *(const PG8_LAS bf16x8*)(lds + PG8_SB(b, h) + boff + n * 2048 + k * 1024); } while (0)
; #define PG8_MMA(ai, bj, At, Bt) do { __builtin_amdgcn_s_setprio(1); _Pragma("unroll") for (int m = 0; m < 4; ++m) _Pragma("unroll") for (int n = 0; n < 2; ++n) _Pragma("unroll") for (int k = 0; k < 2; ++k) \
;         acc[ai][bj][m][n] = __builtin_amdgcn_mfma_f32_16x16x32_bf16(Bt[n][k], At[m][k], acc[ai][bj][m][n], 0, 0, 0); __builtin_amdgcn_s_setprio(0); } while (0)
; #define PG8_WAIT_V(n) asm volatile("s_waitcnt vmcnt(" #n ")" ::: "memory")
; #define PG8_WAIT_L(n) asm volatile("s_waitcnt lgkmcnt(" #n ")" ::: "memory")
; #define PG8_BAR __builtin_amdgcn_s_barrier()
; #define PG8_SCHED __builtin_amdgcn_sched_barrier(0)
; template <class Epi, class Sched, bool ALIGN_EPI = false, bool SP2 = false>
; __device__ __forceinline__ void gemm_phase(PG8_LAS unsigned char* lds, const Gemm g, const Sched& S, const Epi& E) {
;     ...
;             PG8_LDB(B0, 0, 0); PG8_LDB(B1, 0, 1); PG8_SCHED; PG8_LDA(At, 0, 0); PG8_STAGE(PG8_SA(1, 1), a1 + hstep, voffA);
;             PG8_WAIT_V(8); PG8_WAIT_L(0); PG8_BAR; PG8_MMA(0, 0, At, B0); PG8_MMA(0, 1, At, B1); PG8_BAR; PG8_SCHED;
;             PG8_LDA(At, 0, 1); PG8_STAGE(PG8_SB(0, 0), b2, voffB); PG8_STAGE(PG8_SB(0, 1), b2 + hstep, voffB); PG8_STAGE(PG8_SA(0, 0), a2, voffA);
;             PG8_WAIT_V(8); PG8_WAIT_L(0); PG8_BAR; PG8_MMA(1, 0, At, B0); PG8_MMA(1, 1, At, B1); PG8_BAR; PG8_SCHED;
.Lk_peel_b:
	s_add_i32 s82, s8, 2
	s_add_u32 s46, s6, 0x80
	s_addc_u32 s9, s7, 0
	s_cmp_eq_u32 s96, s8
	s_cselect_b32 s9, s79, s9
	s_cselect_b32 s8, s78, s46
	s_cselect_b32 s47, s81, vcc_hi
	s_cselect_b32 s46, s80, vcc_lo
	ds_read_b128 v[142:145], v232
	ds_read_b128 v[146:149], v232 offset:1024
	ds_read_b128 v[174:177], v232 offset:2048
	ds_read_b128 v[178:181], v232 offset:3072
	ds_read_b128 v[182:185], v232 offset:16384
	ds_read_b128 v[186:189], v232 offset:17408
	ds_read_b128 v[190:193], v232 offset:18432
	ds_read_b128 v[194:197], v232 offset:19456
	s_add_i32 m0, s68, 0xc000
	ds_read_b128 v[198:201], v173
	ds_read_b128 v[202:205], v173 offset:1024
	ds_read_b128 v[206:209], v173 offset:2048
	ds_read_b128 v[210:213], v173 offset:3072
	ds_read_b128 v[214:217], v173 offset:4096
	ds_read_b128 v[218:221], v173 offset:5120
	ds_read_b128 v[222:225], v173 offset:6144
	ds_read_b128 v[226:229], v173 offset:7168
	global_load_lds_dwordx4 v140, s[6:7]
	s_add_i32 m0, s68, 0xe000
	s_nop 0
	global_load_lds_dwordx4 v138, s[6:7]
	s_waitcnt vmcnt(24)
	s_waitcnt lgkmcnt(0)
	s_barrier
	s_setprio 1
	v_mfma_f32_16x16x32_bf16 v[124:127], v[142:145], v[198:201], 0
	v_mfma_f32_16x16x32_bf16 v[120:123], v[174:177], v[198:201], 0
	v_mfma_f32_16x16x32_bf16 v[108:111], v[142:145], v[206:209], 0
	v_mfma_f32_16x16x32_bf16 v[104:107], v[174:177], v[206:209], 0
	v_mfma_f32_16x16x32_bf16 v[92:95], v[142:145], v[214:217], 0
	v_mfma_f32_16x16x32_bf16 v[88:91], v[174:177], v[214:217], 0
	v_mfma_f32_16x16x32_bf16 v[76:79], v[142:145], v[222:225], 0
	v_mfma_f32_16x16x32_bf16 v[72:75], v[174:177], v[222:225], 0
	v_mfma_f32_16x16x32_bf16 v[124:127], v[146:149], v[202:205], v[124:127]
	v_mfma_f32_16x16x32_bf16 v[120:123], v[178:181], v[202:205], v[120:123]
	v_mfma_f32_16x16x32_bf16 v[108:111], v[146:149], v[210:213], v[108:111]
	v_mfma_f32_16x16x32_bf16 v[104:107], v[178:181], v[210:213], v[104:107]
	v_mfma_f32_16x16x32_bf16 v[92:95], v[146:149], v[218:221], v[92:95]
	v_mfma_f32_16x16x32_bf16 v[88:91], v[178:181], v[218:221], v[88:91]
	v_mfma_f32_16x16x32_bf16 v[76:79], v[146:149], v[226:229], v[76:79]
	v_mfma_f32_16x16x32_bf16 v[72:75], v[178:181], v[226:229], v[72:75]
	s_setprio 0
	s_setprio 1
	v_mfma_f32_16x16x32_bf16 v[116:119], v[182:185], v[198:201], 0
	v_mfma_f32_16x16x32_bf16 v[112:115], v[190:193], v[198:201], 0
	v_mfma_f32_16x16x32_bf16 v[100:103], v[182:185], v[206:209], 0
	v_mfma_f32_16x16x32_bf16 v[96:99], v[190:193], v[206:209], 0
	v_mfma_f32_16x16x32_bf16 v[84:87], v[182:185], v[214:217], 0
	v_mfma_f32_16x16x32_bf16 v[80:83], v[190:193], v[214:217], 0
	v_mfma_f32_16x16x32_bf16 v[68:71], v[182:185], v[222:225], 0
	v_mfma_f32_16x16x32_bf16 v[64:67], v[190:193], v[222:225], 0
	v_mfma_f32_16x16x32_bf16 v[116:119], v[186:189], v[202:205], v[116:119]
	v_mfma_f32_16x16x32_bf16 v[112:115], v[194:197], v[202:205], v[112:115]
	v_mfma_f32_16x16x32_bf16 v[100:103], v[186:189], v[210:213], v[100:103]
	v_mfma_f32_16x16x32_bf16 v[96:99], v[194:197], v[210:213], v[96:99]
	v_mfma_f32_16x16x32_bf16 v[84:87], v[186:189], v[218:221], v[84:87]
	v_mfma_f32_16x16x32_bf16 v[80:83], v[194:197], v[218:221], v[80:83]
	v_mfma_f32_16x16x32_bf16 v[68:71], v[186:189], v[226:229], v[68:71]
	v_mfma_f32_16x16x32_bf16 v[64:67], v[194:197], v[226:229], v[64:67]
	s_setprio 0
	s_barrier
	s_add_i32 m0, s65, 0x10000
	ds_read_b128 v[198:201], v173 offset:16384
	ds_read_b128 v[202:205], v173 offset:17408
	ds_read_b128 v[206:209], v173 offset:18432
	ds_read_b128 v[210:213], v173 offset:19456
	ds_read_b128 v[214:217], v173 offset:20480
	ds_read_b128 v[218:221], v173 offset:21504
	ds_read_b128 v[222:225], v173 offset:22528
	ds_read_b128 v[226:229], v173 offset:23552
	global_load_lds_dwordx4 v128, s[46:47]
	s_add_i32 m0, s65, 0x12000
	s_nop 0
	global_load_lds_dwordx4 v136, s[46:47]
	s_add_i32 m0, s65, 0x14000
	s_nop 0
	global_load_lds_dwordx4 v230, s[46:47]
	s_add_i32 m0, s65, 0x16000
	s_nop 0
	global_load_lds_dwordx4 v231, s[46:47]
	s_mov_b32 m0, s68
	s_nop 0
	global_load_lds_dwordx4 v132, s[8:9]
	s_mov_b32 m0, s87
	s_nop 0
	global_load_lds_dwordx4 v134, s[8:9]
	s_waitcnt vmcnt(24)
	s_waitcnt lgkmcnt(0)
	s_barrier
	s_setprio 1
	v_mfma_f32_16x16x32_bf16 v[60:63], v[142:145], v[198:201], 0
	v_mfma_f32_16x16x32_bf16 v[56:59], v[174:177], v[198:201], 0
	v_mfma_f32_16x16x32_bf16 v[44:47], v[142:145], v[206:209], 0
	v_mfma_f32_16x16x32_bf16 v[40:43], v[174:177], v[206:209], 0
	v_mfma_f32_16x16x32_bf16 v[28:31], v[142:145], v[214:217], 0
	v_mfma_f32_16x16x32_bf16 v[24:27], v[174:177], v[214:217], 0
	v_mfma_f32_16x16x32_bf16 v[12:15], v[142:145], v[222:225], 0
	v_mfma_f32_16x16x32_bf16 v[8:11], v[174:177], v[222:225], 0
	v_mfma_f32_16x16x32_bf16 v[60:63], v[146:149], v[202:205], v[60:63]
	v_mfma_f32_16x16x32_bf16 v[56:59], v[178:181], v[202:205], v[56:59]
	v_mfma_f32_16x16x32_bf16 v[44:47], v[146:149], v[210:213], v[44:47]
	v_mfma_f32_16x16x32_bf16 v[40:43], v[178:181], v[210:213], v[40:43]
	v_mfma_f32_16x16x32_bf16 v[28:31], v[146:149], v[218:221], v[28:31]
	v_mfma_f32_16x16x32_bf16 v[24:27], v[178:181], v[218:221], v[24:27]
	v_mfma_f32_16x16x32_bf16 v[12:15], v[146:149], v[226:229], v[12:15]
	v_mfma_f32_16x16x32_bf16 v[8:11], v[178:181], v[226:229], v[8:11]
	s_setprio 0
	s_setprio 1
	v_mfma_f32_16x16x32_bf16 v[52:55], v[182:185], v[198:201], 0
	v_mfma_f32_16x16x32_bf16 v[48:51], v[190:193], v[198:201], 0
	v_mfma_f32_16x16x32_bf16 v[36:39], v[182:185], v[206:209], 0
	v_mfma_f32_16x16x32_bf16 v[32:35], v[190:193], v[206:209], 0
	v_mfma_f32_16x16x32_bf16 v[20:23], v[182:185], v[214:217], 0
	v_mfma_f32_16x16x32_bf16 v[16:19], v[190:193], v[214:217], 0
	v_mfma_f32_16x16x32_bf16 v[4:7], v[182:185], v[222:225], 0
	v_mfma_f32_16x16x32_bf16 v[0:3], v[190:193], v[222:225], 0
	v_mfma_f32_16x16x32_bf16 v[52:55], v[186:189], v[202:205], v[52:55]
	v_mfma_f32_16x16x32_bf16 v[48:51], v[194:197], v[202:205], v[48:51]
	v_mfma_f32_16x16x32_bf16 v[36:39], v[186:189], v[210:213], v[36:39]
	v_mfma_f32_16x16x32_bf16 v[32:35], v[194:197], v[210:213], v[32:35]
	v_mfma_f32_16x16x32_bf16 v[20:23], v[186:189], v[218:221], v[20:23]
	v_mfma_f32_16x16x32_bf16 v[16:19], v[194:197], v[218:221], v[16:19]
	v_mfma_f32_16x16x32_bf16 v[4:7], v[186:189], v[226:229], v[4:7]
	v_mfma_f32_16x16x32_bf16 v[0:3], v[194:197], v[226:229], v[0:3]
	s_setprio 0
	s_barrier
; #define PG8_STAGE(bufoff, gbase, voff) do { _Pragma("unroll") for (int _i = 0; _i < 2; ++_i) \
;         __builtin_amdgcn_global_load_lds((const unsigned*)((const char*)(gbase) + (voff)[_i]), (PG8_LAS unsigned*)(lds + (bufoff) + ldsw + _i * 8192), 16, 0, 0); } while (0)
; #define PG8_LDA(dst, b, h) do { _Pragma("unroll") for (int m = 0; m < 4; ++m) _Pragma("unroll") for (int k = 0; k < 2; ++k) dst[m][k] = *(const PG8_LAS bf16x8*)(lds + PG8_SA(b, h) + aoff + m * 2048 + k * 1024); } while (0)
; #define PG8_LDB(dst, b, h) do { _Pragma("unroll") for (int n = 0; n < 2; ++n) _Pragma("unroll") for (int k = 0; k < 2; ++k) dst[n][k] = *(const PG8_LAS bf16x8*)(lds + PG8_SB(b, h) + boff + n * 2048 + k * 1024); } while (0)
; #define PG8_MMA(ai, bj, At, Bt) do { __builtin_amdgcn_s_setprio(1); _Pragma("unroll") for (int m = 0; m < 4; ++m) _Pragma("unroll") for (int n = 0; n < 2; ++n) _Pragma("unroll") for (int k = 0; k < 2; ++k) \
;         acc[ai][bj][m][n] = __builtin_amdgcn_mfma_f32_16x16x32_bf16(Bt[n][k], At[m][k], acc[ai][bj][m][n], 0, 0, 0); __builtin_amdgcn_s_setprio(0); } while (0)
; #define PG8_WAIT_V(n) asm volatile("s_waitcnt vmcnt(" #n ")" ::: "memory")
; #define PG8_WAIT_L(n) asm volatile("s_waitcnt lgkmcnt(" #n ")" ::: "memory")
; #define PG8_BAR __builtin_amdgcn_s_barrier()
; #define PG8_SCHED __builtin_amdgcn_sched_barrier(0)
; template <class Epi, class Sched, bool ALIGN_EPI = false, bool SP2 = false>
; __device__ __forceinline__ void gemm_phase(PG8_LAS unsigned char* lds, const Gemm g, const Sched& S, const Epi& E) {
;     ...
;         for (int t = 0; t < nt; t += 2) {
;     ...
;             PG8_LDB(B0, 1, 0); PG8_LDB(B1, 1, 1); PG8_SCHED; PG8_LDA(At, 1, 0); PG8_STAGE(PG8_SA(0, 1), a2 + hstep, voffA);
;             PG8_WAIT_V(8); PG8_WAIT_L(0); PG8_BAR; PG8_MMA(0, 0, At, B0); PG8_MMA(0, 1, At, B1); PG8_BAR; PG8_SCHED;
;             PG8_LDA(At, 1, 1); PG8_STAGE(PG8_SB(1, 0), b3, voffB); PG8_STAGE(PG8_SB(1, 1), b3 + hstep, voffB); PG8_STAGE(PG8_SA(1, 0), a3, voffA);
;             PG8_WAIT_V(8); PG8_WAIT_L(0); PG8_BAR; PG8_MMA(1, 0, At, B0); PG8_MMA(1, 1, At, B1); PG8_BAR; PG8_SCHED;
	ds_read_b128 v[142:145], v232 offset:32768
	ds_read_b128 v[146:149], v232 offset:33792
	ds_read_b128 v[174:177], v232 offset:34816
	ds_read_b128 v[178:181], v232 offset:35840
	ds_read_b128 v[182:185], v232 offset:49152
	ds_read_b128 v[186:189], v232 offset:50176
	ds_read_b128 v[190:193], v232 offset:51200
	ds_read_b128 v[194:197], v232 offset:52224
	s_mov_b32 m0, s1
	ds_read_b128 v[198:201], v173 offset:32768
	ds_read_b128 v[202:205], v173 offset:33792
	ds_read_b128 v[206:209], v173 offset:34816
	ds_read_b128 v[210:213], v173 offset:35840
	ds_read_b128 v[214:217], v173 offset:36864
	ds_read_b128 v[218:221], v173 offset:37888
	ds_read_b128 v[222:225], v173 offset:38912
	ds_read_b128 v[226:229], v173 offset:39936
	global_load_lds_dwordx4 v140, s[8:9]
	s_mov_b32 m0, s0
	s_nop 0
	global_load_lds_dwordx4 v138, s[8:9]
	s_waitcnt vmcnt(8)
	s_waitcnt lgkmcnt(0)
	s_barrier
	s_setprio 1
	v_mfma_f32_16x16x32_bf16 v[124:127], v[142:145], v[198:201], v[124:127]
	v_mfma_f32_16x16x32_bf16 v[120:123], v[174:177], v[198:201], v[120:123]
	v_mfma_f32_16x16x32_bf16 v[108:111], v[142:145], v[206:209], v[108:111]
	v_mfma_f32_16x16x32_bf16 v[104:107], v[174:177], v[206:209], v[104:107]
	v_mfma_f32_16x16x32_bf16 v[92:95], v[142:145], v[214:217], v[92:95]
	v_mfma_f32_16x16x32_bf16 v[88:91], v[174:177], v[214:217], v[88:91]
	v_mfma_f32_16x16x32_bf16 v[76:79], v[142:145], v[222:225], v[76:79]
	v_mfma_f32_16x16x32_bf16 v[72:75], v[174:177], v[222:225], v[72:75]
	v_mfma_f32_16x16x32_bf16 v[124:127], v[146:149], v[202:205], v[124:127]
	v_mfma_f32_16x16x32_bf16 v[120:123], v[178:181], v[202:205], v[120:123]
	v_mfma_f32_16x16x32_bf16 v[108:111], v[146:149], v[210:213], v[108:111]
	v_mfma_f32_16x16x32_bf16 v[104:107], v[178:181], v[210:213], v[104:107]
	v_mfma_f32_16x16x32_bf16 v[92:95], v[146:149], v[218:221], v[92:95]
	v_mfma_f32_16x16x32_bf16 v[88:91], v[178:181], v[218:221], v[88:91]
	v_mfma_f32_16x16x32_bf16 v[76:79], v[146:149], v[226:229], v[76:79]
	v_mfma_f32_16x16x32_bf16 v[72:75], v[178:181], v[226:229], v[72:75]
	s_setprio 0
	s_setprio 1
	v_mfma_f32_16x16x32_bf16 v[116:119], v[182:185], v[198:201], v[116:119]
	v_mfma_f32_16x16x32_bf16 v[112:115], v[190:193], v[198:201], v[112:115]
	v_mfma_f32_16x16x32_bf16 v[100:103], v[182:185], v[206:209], v[100:103]
	v_mfma_f32_16x16x32_bf16 v[96:99], v[190:193], v[206:209], v[96:99]
	v_mfma_f32_16x16x32_bf16 v[84:87], v[182:185], v[214:217], v[84:87]
	v_mfma_f32_16x16x32_bf16 v[80:83], v[190:193], v[214:217], v[80:83]
	v_mfma_f32_16x16x32_bf16 v[68:71], v[182:185], v[222:225], v[68:71]
	v_mfma_f32_16x16x32_bf16 v[64:67], v[190:193], v[222:225], v[64:67]
	v_mfma_f32_16x16x32_bf16 v[116:119], v[186:189], v[202:205], v[116:119]
	v_mfma_f32_16x16x32_bf16 v[112:115], v[194:197], v[202:205], v[112:115]
	v_mfma_f32_16x16x32_bf16 v[100:103], v[186:189], v[210:213], v[100:103]
	v_mfma_f32_16x16x32_bf16 v[96:99], v[194:197], v[210:213], v[96:99]
	v_mfma_f32_16x16x32_bf16 v[84:87], v[186:189], v[218:221], v[84:87]
	v_mfma_f32_16x16x32_bf16 v[80:83], v[194:197], v[218:221], v[80:83]
	v_mfma_f32_16x16x32_bf16 v[68:71], v[186:189], v[226:229], v[68:71]
	v_mfma_f32_16x16x32_bf16 v[64:67], v[194:197], v[226:229], v[64:67]
	s_setprio 0
	s_barrier
	s_add_i32 m0, s65, 0x17f80
	ds_read_b128 v[198:201], v173 offset:49152
	ds_read_b128 v[202:205], v173 offset:50176
	ds_read_b128 v[206:209], v173 offset:51200
	ds_read_b128 v[210:213], v173 offset:52224
	ds_read_b128 v[214:217], v173 offset:53248
	ds_read_b128 v[218:221], v173 offset:54272
	ds_read_b128 v[222:225], v173 offset:55296
	ds_read_b128 v[226:229], v173 offset:56320
	global_load_lds_dwordx4 v128, s[46:47] offset:128
	s_add_i32 m0, s65, 0x19f80
	s_nop 0
	global_load_lds_dwordx4 v136, s[46:47] offset:128
	s_add_i32 m0, s65, 0x1bf80
	s_nop 0
	global_load_lds_dwordx4 v230, s[46:47] offset:128
	s_add_i32 m0, s65, 0x1df80
	s_nop 0
	global_load_lds_dwordx4 v231, s[46:47] offset:128
	s_add_i32 m0, s88, 0xffffff80
	s_nop 0
	global_load_lds_dwordx4 v132, s[8:9] offset:128
	s_add_i32 m0, s95, 0xffffff80
	s_nop 0
	global_load_lds_dwordx4 v134, s[8:9] offset:128
	s_waitcnt vmcnt(8)
	s_waitcnt lgkmcnt(0)
	s_barrier
	s_setprio 1
	v_mfma_f32_16x16x32_bf16 v[60:63], v[142:145], v[198:201], v[60:63]
	v_mfma_f32_16x16x32_bf16 v[56:59], v[174:177], v[198:201], v[56:59]
	v_mfma_f32_16x16x32_bf16 v[44:47], v[142:145], v[206:209], v[44:47]
	v_mfma_f32_16x16x32_bf16 v[40:43], v[174:177], v[206:209], v[40:43]
	v_mfma_f32_16x16x32_bf16 v[28:31], v[142:145], v[214:217], v[28:31]
	v_mfma_f32_16x16x32_bf16 v[24:27], v[174:177], v[214:217], v[24:27]
	v_mfma_f32_16x16x32_bf16 v[12:15], v[142:145], v[222:225], v[12:15]
	v_mfma_f32_16x16x32_bf16 v[8:11], v[174:177], v[222:225], v[8:11]
	v_mfma_f32_16x16x32_bf16 v[60:63], v[146:149], v[202:205], v[60:63]
	v_mfma_f32_16x16x32_bf16 v[56:59], v[178:181], v[202:205], v[56:59]
	v_mfma_f32_16x16x32_bf16 v[44:47], v[146:149], v[210:213], v[44:47]
	v_mfma_f32_16x16x32_bf16 v[40:43], v[178:181], v[210:213], v[40:43]
	v_mfma_f32_16x16x32_bf16 v[28:31], v[146:149], v[218:221], v[28:31]
	v_mfma_f32_16x16x32_bf16 v[24:27], v[178:181], v[218:221], v[24:27]
	v_mfma_f32_16x16x32_bf16 v[12:15], v[146:149], v[226:229], v[12:15]
	v_mfma_f32_16x16x32_bf16 v[8:11], v[178:181], v[226:229], v[8:11]
	s_setprio 0
	s_setprio 1
	v_mfma_f32_16x16x32_bf16 v[52:55], v[182:185], v[198:201], v[52:55]
	v_mfma_f32_16x16x32_bf16 v[48:51], v[190:193], v[198:201], v[48:51]
	v_mfma_f32_16x16x32_bf16 v[36:39], v[182:185], v[206:209], v[36:39]
	v_mfma_f32_16x16x32_bf16 v[32:35], v[190:193], v[206:209], v[32:35]
	v_mfma_f32_16x16x32_bf16 v[20:23], v[182:185], v[214:217], v[20:23]
	v_mfma_f32_16x16x32_bf16 v[16:19], v[190:193], v[214:217], v[16:19]
	v_mfma_f32_16x16x32_bf16 v[4:7], v[182:185], v[222:225], v[4:7]
	v_mfma_f32_16x16x32_bf16 v[0:3], v[190:193], v[222:225], v[0:3]
	v_mfma_f32_16x16x32_bf16 v[52:55], v[186:189], v[202:205], v[52:55]
	v_mfma_f32_16x16x32_bf16 v[48:51], v[194:197], v[202:205], v[48:51]
	v_mfma_f32_16x16x32_bf16 v[36:39], v[186:189], v[210:213], v[36:39]
	v_mfma_f32_16x16x32_bf16 v[32:35], v[194:197], v[210:213], v[32:35]
	v_mfma_f32_16x16x32_bf16 v[20:23], v[186:189], v[218:221], v[20:23]
	v_mfma_f32_16x16x32_bf16 v[16:19], v[194:197], v[218:221], v[16:19]
	v_mfma_f32_16x16x32_bf16 v[4:7], v[186:189], v[226:229], v[4:7]
	v_mfma_f32_16x16x32_bf16 v[0:3], v[194:197], v[226:229], v[0:3]
	s_setprio 0
	s_barrier
	s_add_u32 vcc_lo, vcc_lo, 0x100
	s_addc_u32 vcc_hi, vcc_hi, 0
	s_add_u32 s6, s6, 0x100
	s_addc_u32 s7, s7, 0
	s_cmp_ge_u32 s82, s97
	s_mov_b32 s8, s82
	s_cbranch_scc1 .Lk_done

;     __device__ __forceinline__ void operator()(const f32x4 (&acc)[2][2][4][2], const Unit& u, int wr, int wc, int fr, int fq) const {
;         const int row0 = u.pm * BM + wr * 64 + fr; const int col0 = u.pn * BM + wc * 32 + 8 * fq;
; #pragma unroll
;         for (int ai = 0; ai < 2; ++ai)
; #pragma unroll
;             for (int m = 0; m < 4; ++m) { const int row = row0 + ai * HALF + m * 16; bf16_t* rowp = O + (size_t)row * ldc + col0;
;                 const float sc = rs ? rs[row] : 1.0f;
.Lk_done:
	v_lshl_add_u32 v142, s71, 8, v131
	v_mov_b32_e32 v143, 0
	v_lshl_or_b32 v191, s91, 8, v172
	s_lshl_b32 s46, s60, 5
	v_mul_lo_u32 v190, v142, s60
	s_mul_i32 s47, s46, 5
	s_andn2_b64 vcc, exec, s[76:77]
	v_add_lshl_u32 v190, v190, v191, 1
	s_cbranch_vccnz .Lepi_nors
	v_lshl_add_u64 v[144:145], v[142:143], 2, s[36:37]
	global_load_dword v174, v[144:145], off
	global_load_dword v176, v[144:145], off offset:64
	global_load_dword v178, v[144:145], off offset:128
	global_load_dword v180, v[144:145], off offset:192
	global_load_dword v182, v[144:145], off offset:512
	global_load_dword v184, v[144:145], off offset:576
	global_load_dword v186, v[144:145], off offset:640
	global_load_dword v188, v[144:145], off offset:704
	s_branch .Lepi_bar
